# v15: v8 + conv tap weights kept resident in registers (reload only when channel group changes; no prefetch drain) + attention QK LDS-read pipelining + sgu u/bias loads hoisted before prefetch; bit-exa
# speedup vs baseline: 1.0022x; 1.0022x over previous
; #define LAS __attribute__((address_space(3)))
; __device__ __forceinline__ unsigned cvt_pk_bf16(float lo, float hi) { unsigned r; asm("v_cvt_pk_bf16_f32 %0, %1, %2" : "=v"(r) : "v"(lo), "v"(hi)); return r; }
; __device__ __forceinline__ float bf_lo(unsigned u) { return __uint_as_float(u << 16); }
; __device__ __forceinline__ float bf_hi(unsigned u) { return __uint_as_float(u & 0xffff0000u); }
; __device__ __forceinline__ void sgu_phase(LAS unsigned char* lds, const bf16_t* U, const bf16_t* VTg, const float* vg, const float* vb, const float* wsp, const float* bsp, bf16_t* Gout, int bid, int G, const int tid) {
;     ...
;             for (int i = 0; i < 8; ++i) {
;                 const int idx = tid + 512 * i, t = idx >> 5, s4 = (idx & 31) * 4;
;                 f32x4 v = wreg[i];
; #pragma unroll
;                 for (int e = 0; e < 4; ++e) if (s4 + e > t) v[e] = 0.f;
;                 u32x2 o; o.x = cvt_pk_bf16(v[0], v[1]); o.y = cvt_pk_bf16(v[2], v[3]);
;                 *(LAS u32x2*)(Ws + t * RS + s4) = o;
;             }
; #pragma unroll
;             for (int i = 0; i < 8; ++i) {
;                 const int idx = tid + 512 * i, d = idx >> 4, tc = idx & 15;
;                 const u32x4 t = vreg[i];
;                 const float ga = gar[i], be = ber[i];
;                 float v[8] = {bf_lo(t.x), bf_hi(t.x), bf_lo(t.y), bf_hi(t.y), bf_lo(t.z), bf_hi(t.z), bf_lo(t.w), bf_hi(t.w)};
; #pragma unroll
;                 for (int e = 0; e < 8; ++e) { const f32x2 ms = *(const LAS f32x2*)(st + (tc * 8 + e) * 2); v[e] = (v[e] - ms[0]) * ms[1] * ga + be; }
;                 u32x4 o; o.x = cvt_pk_bf16(v[0], v[1]); o.y = cvt_pk_bf16(v[2], v[3]); o.z = cvt_pk_bf16(v[4], v[5]); o.w = cvt_pk_bf16(v[6], v[7]);
;                 *(LAS u32x4*)(Vs + d * RS + tc * 8) = o;
.LBB0_128:
	v_mov_b32_e32 v64, s27
	s_waitcnt vmcnt(0) lgkmcnt(0)
	v_cndmask_b32_e64 v64, v0, v64, s[40:41]
	v_cndmask_b32_e64 v64, v64, v0, s[42:43]
	v_cndmask_b32_e64 v65, 0, v1, s[42:43]
	v_cvt_pk_bf16_f32 v64, v64, v65
	v_cndmask_b32_e64 v66, v2, 0, s[44:45]
	v_cndmask_b32_e64 v67, v3, 0, s[46:47]
	v_cvt_pk_bf16_f32 v65, v66, v67
	ds_write_b64 v160, v[64:65]
	v_mov_b32_e32 v64, s27
	v_cndmask_b32_e64 v64, v8, v64, s[48:49]
	v_cndmask_b32_e64 v64, v64, v8, s[50:51]
	v_cndmask_b32_e64 v65, 0, v9, s[50:51]
	v_cvt_pk_bf16_f32 v64, v64, v65
	v_cndmask_b32_e64 v66, v10, 0, s[52:53]
	v_cndmask_b32_e64 v67, v11, 0, s[54:55]
	v_cvt_pk_bf16_f32 v65, v66, v67
	ds_write_b64 v161, v[64:65]
	v_mov_b32_e32 v64, s27
	v_cndmask_b32_e64 v64, v16, v64, s[56:57]
	v_cndmask_b32_e64 v64, v64, v16, s[58:59]
	v_cndmask_b32_e64 v65, 0, v17, s[58:59]
	v_cvt_pk_bf16_f32 v64, v64, v65
	v_cndmask_b32_e64 v66, v18, 0, s[60:61]
	v_cndmask_b32_e64 v67, v19, 0, s[62:63]
	v_cvt_pk_bf16_f32 v65, v66, v67
	ds_write_b64 v162, v[64:65]
	v_mov_b32_e32 v64, s27
	v_cndmask_b32_e64 v64, v24, v64, s[64:65]
	v_cndmask_b32_e64 v64, v64, v24, s[66:67]
	v_cndmask_b32_e64 v65, 0, v25, s[66:67]
	v_cvt_pk_bf16_f32 v64, v64, v65
	v_cndmask_b32_e64 v66, v26, 0, s[68:69]
	v_cndmask_b32_e64 v67, v27, 0, s[70:71]
	v_cvt_pk_bf16_f32 v65, v66, v67
	ds_write_b64 v163, v[64:65]
	v_mov_b32_e32 v64, s27
	v_cndmask_b32_e64 v64, v32, v64, s[72:73]
	v_cndmask_b32_e64 v64, v64, v32, s[74:75]
	v_cndmask_b32_e64 v65, 0, v33, s[74:75]
	v_cvt_pk_bf16_f32 v64, v64, v65
	v_cndmask_b32_e64 v66, v34, 0, s[76:77]
	v_cndmask_b32_e64 v67, v35, 0, s[78:79]
	v_cvt_pk_bf16_f32 v65, v66, v67
	ds_write_b64 v164, v[64:65]
	v_mov_b32_e32 v64, s27
	v_cndmask_b32_e64 v64, v40, v64, s[80:81]
	v_cndmask_b32_e64 v64, v64, v40, s[82:83]
	v_cndmask_b32_e64 v65, 0, v41, s[82:83]
	v_cvt_pk_bf16_f32 v64, v64, v65
	v_cndmask_b32_e64 v66, v42, 0, s[84:85]
	v_cndmask_b32_e64 v67, v43, 0, s[86:87]
	v_cvt_pk_bf16_f32 v65, v66, v67
	ds_write_b64 v165, v[64:65]
	v_mov_b32_e32 v64, s27
	v_cndmask_b32_e64 v64, v48, v64, s[88:89]
	v_cndmask_b32_e64 v64, v64, v48, s[90:91]
	v_cndmask_b32_e64 v65, 0, v49, s[90:91]
	v_cvt_pk_bf16_f32 v64, v64, v65
	v_cndmask_b32_e64 v66, v50, 0, s[92:93]
	v_cndmask_b32_e64 v67, v51, 0, s[94:95]
	v_cvt_pk_bf16_f32 v65, v66, v67
	ds_write_b64 v166, v[64:65]
	v_mov_b32_e32 v64, s27
	v_cndmask_b32_e64 v64, v56, v64, s[96:97]
	v_cndmask_b32_e64 v64, v64, v56, s[98:99]
	v_cndmask_b32_e64 v65, 0, v57, s[98:99]
	v_cvt_pk_bf16_f32 v64, v64, v65
	v_cndmask_b32_e64 v66, v58, 0, s[6:7]
	v_cndmask_b32_e64 v67, v59, 0, s[4:5]
	v_cvt_pk_bf16_f32 v65, v66, v67
	ds_write_b64 v167, v[64:65]
	v_add_u32_e32 v64, 0, v153
	v_add_u32_e32 v87, 0x19800, v64
	ds_read_b128 v[64:67], v87
	ds_read_b128 v[68:71], v87 offset:16
	ds_read_b128 v[72:75], v87 offset:32
	ds_read_b128 v[76:79], v87 offset:48
	v_lshlrev_b32_e32 v80, 16, v4
	v_and_b32_e32 v81, 0xffff0000, v4
	v_lshlrev_b32_e32 v82, 16, v5
	s_waitcnt lgkmcnt(3)
	v_sub_f32_e32 v64, v80, v64
	v_and_b32_e32 v83, 0xffff0000, v5
	v_mul_f32_e32 v64, v65, v64
	v_sub_f32_e32 v65, v81, v66
	v_lshlrev_b32_e32 v84, 16, v6
	v_and_b32_e32 v85, 0xffff0000, v6
	v_lshlrev_b32_e32 v86, 16, v7
	v_and_b32_e32 v88, 0xffff0000, v7
	v_mul_f32_e32 v65, v67, v65
	s_waitcnt lgkmcnt(2)
	v_sub_f32_e32 v66, v82, v68
	v_sub_f32_e32 v67, v83, v70
	v_mul_f32_e32 v66, v69, v66
	v_mul_f32_e32 v67, v71, v67
	s_waitcnt lgkmcnt(1)
	v_sub_f32_e32 v68, v84, v72
	v_sub_f32_e32 v69, v85, v74
	s_waitcnt lgkmcnt(0)
	v_sub_f32_e32 v70, v86, v76
	v_sub_f32_e32 v71, v88, v78
	v_fma_f32 v64, v176, v64, v186
	v_fma_f32 v65, v176, v65, v186
	v_fma_f32 v66, v176, v66, v186
	v_fma_f32 v67, v176, v67, v186
	v_mul_f32_e32 v68, v73, v68
	v_mul_f32_e32 v69, v75, v69
	v_mul_f32_e32 v70, v77, v70
	v_mul_f32_e32 v71, v79, v71
	v_fma_f32 v68, v176, v68, v186
	v_fma_f32 v69, v176, v69, v186
	v_fma_f32 v70, v176, v70, v186
	v_fma_f32 v71, v176, v71, v186
	v_cvt_pk_bf16_f32 v64, v64, v65
	v_cvt_pk_bf16_f32 v65, v66, v67
	v_cvt_pk_bf16_f32 v66, v68, v69
	v_cvt_pk_bf16_f32 v67, v70, v71
	ds_write_b128 v168, v[64:67] offset:34816
	ds_read_b128 v[64:67], v87
	ds_read_b128 v[68:71], v87 offset:16
	ds_read_b128 v[72:75], v87 offset:32
	ds_read_b128 v[76:79], v87 offset:48
	v_lshlrev_b32_e32 v80, 16, v12
	v_and_b32_e32 v81, 0xffff0000, v12
	v_lshlrev_b32_e32 v82, 16, v13
	s_waitcnt lgkmcnt(3)
	v_sub_f32_e32 v64, v80, v64
	v_and_b32_e32 v83, 0xffff0000, v13
	v_mul_f32_e32 v64, v65, v64
	v_sub_f32_e32 v65, v81, v66
	v_lshlrev_b32_e32 v84, 16, v14
	v_and_b32_e32 v85, 0xffff0000, v14
	v_lshlrev_b32_e32 v86, 16, v15
	v_and_b32_e32 v88, 0xffff0000, v15
	v_mul_f32_e32 v65, v67, v65
	s_waitcnt lgkmcnt(2)
	v_sub_f32_e32 v66, v82, v68
	v_sub_f32_e32 v67, v83, v70
	v_mul_f32_e32 v66, v69, v66
	v_mul_f32_e32 v67, v71, v67
	s_waitcnt lgkmcnt(1)
	v_sub_f32_e32 v68, v84, v72
	v_sub_f32_e32 v69, v85, v74
	s_waitcnt lgkmcnt(0)
	v_sub_f32_e32 v70, v86, v76
	v_sub_f32_e32 v71, v88, v78
	v_fma_f32 v64, v178, v64, v187
	v_fma_f32 v65, v178, v65, v187
	v_fma_f32 v66, v178, v66, v187
	v_fma_f32 v67, v178, v67, v187
	v_mul_f32_e32 v68, v73, v68
	v_mul_f32_e32 v69, v75, v69
	v_mul_f32_e32 v70, v77, v70
	v_mul_f32_e32 v71, v79, v71
	v_fma_f32 v68, v178, v68, v187
	v_fma_f32 v69, v178, v69, v187
	v_fma_f32 v70, v178, v70, v187
	v_fma_f32 v71, v178, v71, v187
	v_cvt_pk_bf16_f32 v64, v64, v65
	v_cvt_pk_bf16_f32 v65, v66, v67
	v_cvt_pk_bf16_f32 v66, v68, v69
	v_cvt_pk_bf16_f32 v67, v70, v71
	ds_write_b128 v169, v[64:67] offset:34816
	ds_read_b128 v[64:67], v87
	ds_read_b128 v[68:71], v87 offset:16
	ds_read_b128 v[72:75], v87 offset:32
	ds_read_b128 v[76:79], v87 offset:48
	v_lshlrev_b32_e32 v80, 16, v20
	v_and_b32_e32 v81, 0xffff0000, v20
	v_lshlrev_b32_e32 v82, 16, v21
	s_waitcnt lgkmcnt(3)
; #define LAS __attribute__((address_space(3)))
; __device__ __forceinline__ unsigned cvt_pk_bf16(float lo, float hi) { unsigned r; asm("v_cvt_pk_bf16_f32 %0, %1, %2" : "=v"(r) : "v"(lo), "v"(hi)); return r; }
; __device__ __forceinline__ float bf_lo(unsigned u) { return __uint_as_float(u << 16); }
; __device__ __forceinline__ float bf_hi(unsigned u) { return __uint_as_float(u & 0xffff0000u); }
; __device__ __forceinline__ void sgu_phase(LAS unsigned char* lds, const bf16_t* U, const bf16_t* VTg, const float* vg, const float* vb, const float* wsp, const float* bsp, bf16_t* Gout, int bid, int G, const int tid) {
;     ...
;             for (int i = 0; i < 8; ++i) {
;                 const int idx = tid + 512 * i, d = idx >> 4, tc = idx & 15;
;                 const u32x4 t = vreg[i];
;                 const float ga = gar[i], be = ber[i];
;                 float v[8] = {bf_lo(t.x), bf_hi(t.x), bf_lo(t.y), bf_hi(t.y), bf_lo(t.z), bf_hi(t.z), bf_lo(t.w), bf_hi(t.w)};
; #pragma unroll
;                 for (int e = 0; e < 8; ++e) { const f32x2 ms = *(const LAS f32x2*)(st + (tc * 8 + e) * 2); v[e] = (v[e] - ms[0]) * ms[1] * ga + be; }
;                 u32x4 o; o.x = cvt_pk_bf16(v[0], v[1]); o.y = cvt_pk_bf16(v[2], v[3]); o.z = cvt_pk_bf16(v[4], v[5]); o.w = cvt_pk_bf16(v[6], v[7]);
;                 *(LAS u32x4*)(Vs + d * RS + tc * 8) = o;
	v_sub_f32_e32 v64, v80, v64
	v_and_b32_e32 v83, 0xffff0000, v21
	v_mul_f32_e32 v64, v65, v64
	v_sub_f32_e32 v65, v81, v66
	v_lshlrev_b32_e32 v84, 16, v22
	v_and_b32_e32 v85, 0xffff0000, v22
	v_lshlrev_b32_e32 v86, 16, v23
	v_and_b32_e32 v88, 0xffff0000, v23
	v_mul_f32_e32 v65, v67, v65
	s_waitcnt lgkmcnt(2)
	v_sub_f32_e32 v66, v82, v68
	v_sub_f32_e32 v67, v83, v70
	v_mul_f32_e32 v66, v69, v66
	v_mul_f32_e32 v67, v71, v67
	s_waitcnt lgkmcnt(1)
	v_sub_f32_e32 v68, v84, v72
	v_sub_f32_e32 v69, v85, v74
	s_waitcnt lgkmcnt(0)
	v_sub_f32_e32 v70, v86, v76
	v_sub_f32_e32 v71, v88, v78
	v_fma_f32 v64, v180, v64, v188
	v_fma_f32 v65, v180, v65, v188
	v_fma_f32 v66, v180, v66, v188
	v_fma_f32 v67, v180, v67, v188
	v_mul_f32_e32 v68, v73, v68
	v_mul_f32_e32 v69, v75, v69
	v_mul_f32_e32 v70, v77, v70
	v_mul_f32_e32 v71, v79, v71
	v_fma_f32 v68, v180, v68, v188
	v_fma_f32 v69, v180, v69, v188
	v_fma_f32 v70, v180, v70, v188
	v_fma_f32 v71, v180, v71, v188
	v_cvt_pk_bf16_f32 v64, v64, v65
	v_cvt_pk_bf16_f32 v65, v66, v67
	v_cvt_pk_bf16_f32 v66, v68, v69
	v_cvt_pk_bf16_f32 v67, v70, v71
	ds_write_b128 v170, v[64:67] offset:34816
	ds_read_b128 v[64:67], v87
	ds_read_b128 v[68:71], v87 offset:16
	ds_read_b128 v[72:75], v87 offset:32
	ds_read_b128 v[76:79], v87 offset:48
	v_lshlrev_b32_e32 v80, 16, v28
	v_and_b32_e32 v81, 0xffff0000, v28
	v_lshlrev_b32_e32 v82, 16, v29
	s_waitcnt lgkmcnt(3)
	v_sub_f32_e32 v64, v80, v64
	v_and_b32_e32 v83, 0xffff0000, v29
	v_mul_f32_e32 v64, v65, v64
	v_sub_f32_e32 v65, v81, v66
	v_lshlrev_b32_e32 v84, 16, v30
	v_and_b32_e32 v85, 0xffff0000, v30
	v_lshlrev_b32_e32 v86, 16, v31
	v_and_b32_e32 v88, 0xffff0000, v31
	v_mul_f32_e32 v65, v67, v65
	s_waitcnt lgkmcnt(2)
	v_sub_f32_e32 v66, v82, v68
	v_sub_f32_e32 v67, v83, v70
	v_mul_f32_e32 v66, v69, v66
	v_mul_f32_e32 v67, v71, v67
	s_waitcnt lgkmcnt(1)
	v_sub_f32_e32 v68, v84, v72
	v_sub_f32_e32 v69, v85, v74
	s_waitcnt lgkmcnt(0)
	v_sub_f32_e32 v70, v86, v76
	v_sub_f32_e32 v71, v88, v78
	v_fma_f32 v64, v181, v64, v190
	v_fma_f32 v65, v181, v65, v190
	v_fma_f32 v66, v181, v66, v190
	v_fma_f32 v67, v181, v67, v190
	v_mul_f32_e32 v68, v73, v68
	v_mul_f32_e32 v69, v75, v69
	v_mul_f32_e32 v70, v77, v70
	v_mul_f32_e32 v71, v79, v71
	v_fma_f32 v68, v181, v68, v190
	v_fma_f32 v69, v181, v69, v190
	v_fma_f32 v70, v181, v70, v190
	v_fma_f32 v71, v181, v71, v190
	v_cvt_pk_bf16_f32 v64, v64, v65
	v_cvt_pk_bf16_f32 v65, v66, v67
	v_cvt_pk_bf16_f32 v66, v68, v69
	v_cvt_pk_bf16_f32 v67, v70, v71
	ds_write_b128 v171, v[64:67] offset:34816
	ds_read_b128 v[64:67], v87
	ds_read_b128 v[68:71], v87 offset:16
	ds_read_b128 v[72:75], v87 offset:32
	ds_read_b128 v[76:79], v87 offset:48
	v_lshlrev_b32_e32 v80, 16, v36
	v_and_b32_e32 v81, 0xffff0000, v36
	v_lshlrev_b32_e32 v82, 16, v37
	s_waitcnt lgkmcnt(3)
	v_sub_f32_e32 v64, v80, v64
	v_and_b32_e32 v83, 0xffff0000, v37
	v_mul_f32_e32 v64, v65, v64
	v_sub_f32_e32 v65, v81, v66
	v_lshlrev_b32_e32 v84, 16, v38
	v_and_b32_e32 v85, 0xffff0000, v38
	v_lshlrev_b32_e32 v86, 16, v39
	v_and_b32_e32 v88, 0xffff0000, v39
	v_mul_f32_e32 v65, v67, v65
	s_waitcnt lgkmcnt(2)
	v_sub_f32_e32 v66, v82, v68
	v_sub_f32_e32 v67, v83, v70
	v_mul_f32_e32 v66, v69, v66
	v_mul_f32_e32 v67, v71, v67
	s_waitcnt lgkmcnt(1)
	v_sub_f32_e32 v68, v84, v72
	v_sub_f32_e32 v69, v85, v74
	s_waitcnt lgkmcnt(0)
	v_sub_f32_e32 v70, v86, v76
	v_sub_f32_e32 v71, v88, v78
	v_fma_f32 v64, v182, v64, v191
	v_fma_f32 v65, v182, v65, v191
	v_fma_f32 v66, v182, v66, v191
	v_fma_f32 v67, v182, v67, v191
	v_mul_f32_e32 v68, v73, v68
	v_mul_f32_e32 v69, v75, v69
	v_mul_f32_e32 v70, v77, v70
	v_mul_f32_e32 v71, v79, v71
	v_fma_f32 v68, v182, v68, v191
	v_fma_f32 v69, v182, v69, v191
	v_fma_f32 v70, v182, v70, v191
	v_fma_f32 v71, v182, v71, v191
	v_cvt_pk_bf16_f32 v64, v64, v65
	v_cvt_pk_bf16_f32 v65, v66, v67
	v_cvt_pk_bf16_f32 v66, v68, v69
	v_cvt_pk_bf16_f32 v67, v70, v71
	ds_write_b128 v172, v[64:67] offset:34816
	ds_read_b128 v[64:67], v87
	ds_read_b128 v[68:71], v87 offset:16
	ds_read_b128 v[72:75], v87 offset:32
	ds_read_b128 v[76:79], v87 offset:48
	v_lshlrev_b32_e32 v80, 16, v44
	v_and_b32_e32 v81, 0xffff0000, v44
	v_lshlrev_b32_e32 v82, 16, v45
	s_waitcnt lgkmcnt(3)
	v_sub_f32_e32 v64, v80, v64
	v_and_b32_e32 v83, 0xffff0000, v45
	v_mul_f32_e32 v64, v65, v64
	v_sub_f32_e32 v65, v81, v66
	v_lshlrev_b32_e32 v84, 16, v46
	v_and_b32_e32 v85, 0xffff0000, v46
	v_lshlrev_b32_e32 v86, 16, v47
	v_and_b32_e32 v88, 0xffff0000, v47
	v_mul_f32_e32 v65, v67, v65
	s_waitcnt lgkmcnt(2)
	v_sub_f32_e32 v66, v82, v68
	v_sub_f32_e32 v67, v83, v70
	v_mul_f32_e32 v66, v69, v66
	v_mul_f32_e32 v67, v71, v67
	s_waitcnt lgkmcnt(1)
	v_sub_f32_e32 v68, v84, v72
	v_sub_f32_e32 v69, v85, v74
	s_waitcnt lgkmcnt(0)
	v_sub_f32_e32 v70, v86, v76
	v_sub_f32_e32 v71, v88, v78
	v_fma_f32 v64, v183, v64, v192
	v_fma_f32 v65, v183, v65, v192
	v_fma_f32 v66, v183, v66, v192
	v_fma_f32 v67, v183, v67, v192
	v_mul_f32_e32 v68, v73, v68
	v_mul_f32_e32 v69, v75, v69
	v_mul_f32_e32 v70, v77, v70
	v_mul_f32_e32 v71, v79, v71
	v_fma_f32 v68, v183, v68, v192
	v_fma_f32 v69, v183, v69, v192
	v_fma_f32 v70, v183, v70, v192
	v_fma_f32 v71, v183, v71, v192
	v_cvt_pk_bf16_f32 v64, v64, v65
	v_cvt_pk_bf16_f32 v65, v66, v67
	v_cvt_pk_bf16_f32 v66, v68, v69
	v_cvt_pk_bf16_f32 v67, v70, v71
	ds_write_b128 v173, v[64:67] offset:34816
	ds_read_b128 v[64:67], v87
	ds_read_b128 v[68:71], v87 offset:16
	ds_read_b128 v[72:75], v87 offset:32
	ds_read_b128 v[76:79], v87 offset:48
	v_lshlrev_b32_e32 v80, 16, v52
	v_and_b32_e32 v81, 0xffff0000, v52
	v_lshlrev_b32_e32 v82, 16, v53
	s_waitcnt lgkmcnt(3)
; #define LAS __attribute__((address_space(3)))
; __device__ __forceinline__ void sgu_phase(LAS unsigned char* lds, const bf16_t* U, const bf16_t* VTg, const float* vg, const float* vb, const float* wsp, const float* bsp, bf16_t* Gout, int bid, int G, const int tid) {
;     ...
;                 *(LAS u32x4*)(Vs + d * RS + tc * 8) = o;
;             }
;             __syncthreads();
;             if (g + 1 < 8) SGU_LOAD(g + 1);
; #pragma unroll 1
;             for (int hf = 0; hf < 2; ++hf) {
;                 u32x2 ureg[8];
;                 const int t = 16 * w + fr;
;                 const unsigned voffU = (unsigned)((t * D + fq * 4) * 2);
;                 const char* bu = (const char*)(U + r0 * D + g * 256 + hf * 128); char* bg = (char*)(Gout + r0 * D + g * 256 + hf * 128);
; #pragma unroll
;                 for (int d = 0; d < 8; ++d) ureg[d] = *(const u32x2*)(bu + voffU + d * 32);
	v_sub_f32_e32 v64, v80, v64
	v_and_b32_e32 v83, 0xffff0000, v53
	v_mul_f32_e32 v64, v65, v64
	v_sub_f32_e32 v65, v81, v66
	v_lshlrev_b32_e32 v84, 16, v54
	v_and_b32_e32 v85, 0xffff0000, v54
	v_lshlrev_b32_e32 v86, 16, v55
	v_and_b32_e32 v88, 0xffff0000, v55
	v_mul_f32_e32 v65, v67, v65
	s_waitcnt lgkmcnt(2)
	v_sub_f32_e32 v66, v82, v68
	v_sub_f32_e32 v67, v83, v70
	v_mul_f32_e32 v66, v69, v66
	v_mul_f32_e32 v67, v71, v67
	s_waitcnt lgkmcnt(1)
	v_sub_f32_e32 v68, v84, v72
	v_sub_f32_e32 v69, v85, v74
	s_waitcnt lgkmcnt(0)
	v_sub_f32_e32 v70, v86, v76
	v_sub_f32_e32 v71, v88, v78
	v_fma_f32 v64, v184, v64, v194
	v_fma_f32 v65, v184, v65, v194
	v_fma_f32 v66, v184, v66, v194
	v_fma_f32 v67, v184, v67, v194
	v_mul_f32_e32 v68, v73, v68
	v_mul_f32_e32 v69, v75, v69
	v_mul_f32_e32 v70, v77, v70
	v_mul_f32_e32 v71, v79, v71
	v_fma_f32 v68, v184, v68, v194
	v_fma_f32 v69, v184, v69, v194
	v_fma_f32 v70, v184, v70, v194
	v_fma_f32 v71, v184, v71, v194
	v_cvt_pk_bf16_f32 v64, v64, v65
	v_cvt_pk_bf16_f32 v65, v66, v67
	v_cvt_pk_bf16_f32 v66, v68, v69
	v_cvt_pk_bf16_f32 v67, v70, v71
	ds_write_b128 v174, v[64:67] offset:34816
	ds_read_b128 v[64:67], v87
	ds_read_b128 v[68:71], v87 offset:16
	ds_read_b128 v[72:75], v87 offset:32
	ds_read_b128 v[76:79], v87 offset:48
	v_lshlrev_b32_e32 v80, 16, v60
	v_and_b32_e32 v81, 0xffff0000, v60
	v_lshlrev_b32_e32 v82, 16, v61
	s_waitcnt lgkmcnt(3)
	v_sub_f32_e32 v64, v80, v64
	v_and_b32_e32 v83, 0xffff0000, v61
	v_mul_f32_e32 v64, v65, v64
	v_sub_f32_e32 v65, v81, v66
	v_lshlrev_b32_e32 v84, 16, v62
	v_and_b32_e32 v85, 0xffff0000, v62
	v_lshlrev_b32_e32 v86, 16, v63
	v_and_b32_e32 v88, 0xffff0000, v63
	v_mul_f32_e32 v65, v67, v65
	s_waitcnt lgkmcnt(2)
	v_sub_f32_e32 v66, v82, v68
	v_sub_f32_e32 v67, v83, v70
	v_mul_f32_e32 v66, v69, v66
	v_mul_f32_e32 v67, v71, v67
	s_waitcnt lgkmcnt(1)
	v_sub_f32_e32 v68, v84, v72
	v_sub_f32_e32 v69, v85, v74
	s_waitcnt lgkmcnt(0)
	v_sub_f32_e32 v70, v86, v76
	v_sub_f32_e32 v71, v88, v78
	s_add_i32 s3, s15, 1
	v_fma_f32 v64, v185, v64, v195
	v_fma_f32 v65, v185, v65, v195
	v_fma_f32 v66, v185, v66, v195
	v_fma_f32 v67, v185, v67, v195
	v_mul_f32_e32 v68, v73, v68
	v_mul_f32_e32 v69, v75, v69
	v_mul_f32_e32 v70, v77, v70
	v_mul_f32_e32 v71, v79, v71
	s_cmp_lg_u32 s15, 7
	v_fma_f32 v68, v185, v68, v195
	v_fma_f32 v69, v185, v69, v195
	v_fma_f32 v70, v185, v70, v195
	v_fma_f32 v71, v185, v71, v195
	v_cvt_pk_bf16_f32 v64, v64, v65
	v_cvt_pk_bf16_f32 v65, v66, v67
	v_cvt_pk_bf16_f32 v66, v68, v69
	v_cvt_pk_bf16_f32 v67, v70, v71
	ds_write_b128 v175, v[64:67] offset:34816
	s_waitcnt lgkmcnt(0)
	s_barrier
	s_cbranch_scc0 .Lsgu_last
	v_lshl_add_u32 v64, s15, 7, v155
	s_lshl_b32 s26, s15, 9
	v_ashrrev_i32_e32 v65, 31, v64
	v_lshl_add_u64 v[130:131], v[126:127], 0, s[26:27]
	v_lshl_add_u64 v[132:133], v[64:65], 2, s[38:39]
	global_load_dwordx2 v[150:151], v[130:131], off
	global_load_dwordx2 v[148:149], v[130:131], off offset:32
	global_load_dwordx2 v[146:147], v[130:131], off offset:64
	global_load_dwordx2 v[144:145], v[130:131], off offset:96
	global_load_dwordx2 v[142:143], v[130:131], off offset:128
	global_load_dwordx2 v[140:141], v[130:131], off offset:160
	global_load_dwordx2 v[138:139], v[130:131], off offset:192
	global_load_dwordx2 v[136:137], v[130:131], off offset:224
	global_load_dwordx2 v[210:211], v[130:131], off offset:256
	global_load_dwordx2 v[212:213], v[130:131], off offset:288
	global_load_dwordx2 v[214:215], v[130:131], off offset:320
	global_load_dwordx2 v[216:217], v[130:131], off offset:352
	global_load_dwordx2 v[218:219], v[130:131], off offset:384
	global_load_dwordx2 v[220:221], v[130:131], off offset:416
	global_load_dwordx2 v[222:223], v[130:131], off offset:448
	global_load_dwordx2 v[224:225], v[130:131], off offset:480
	global_load_dword v252, v[132:133], off
	s_lshl_b32 s26, s3, 14
	v_lshl_add_u64 v[56:57], s[26:27], 2, v[98:99]
	s_lshl_b32 s26, s3, 8
	s_movk_i32 s17, 0x2000
	s_lshl_b64 s[30:31], s[26:27], 2
	s_lshl_b32 s26, s3, 24
	v_add_co_u32_e32 v8, vcc, s17, v56
	v_lshl_add_u64 v[60:61], v[124:125], 0, s[26:27]
	s_nop 0
	v_addc_co_u32_e32 v9, vcc, 0, v57, vcc
	s_mov_b32 s17, 0x200000
	v_add_co_u32_e32 v12, vcc, s17, v60
	s_movk_i32 s17, 0x4000
	s_nop 0
	v_addc_co_u32_e32 v13, vcc, 0, v61, vcc
	v_add_co_u32_e32 v16, vcc, s17, v56
	s_mov_b32 s17, 0x400000
	s_nop 0
	v_addc_co_u32_e32 v17, vcc, 0, v57, vcc
	v_add_co_u32_e32 v20, vcc, s17, v60
	s_movk_i32 s17, 0x6000
	s_nop 0
	v_addc_co_u32_e32 v21, vcc, 0, v61, vcc
	v_add_co_u32_e32 v24, vcc, s17, v56
	s_mov_b32 s17, 0x600000
	s_nop 0
	v_addc_co_u32_e32 v25, vcc, 0, v57, vcc
	v_add_co_u32_e32 v28, vcc, s17, v60
	s_mov_b32 s17, 0x800000
	s_nop 0
	v_addc_co_u32_e32 v29, vcc, 0, v61, vcc
	v_add_co_u32_e32 v32, vcc, s1, v56
	flat_load_dwordx4 v[0:3], v[56:57]
	s_nop 0
	v_addc_co_u32_e32 v33, vcc, 0, v57, vcc
	v_add_co_u32_e32 v36, vcc, s17, v60
	s_mov_b32 s17, 0xa00000
	s_nop 0
	v_addc_co_u32_e32 v37, vcc, 0, v61, vcc
	v_add_co_u32_e32 v40, vcc, 0xa000, v56
	flat_load_dwordx4 v[4:7], v[60:61]
	s_nop 0
	v_addc_co_u32_e32 v41, vcc, 0, v57, vcc
	v_add_co_u32_e32 v44, vcc, s17, v60
	v_lshl_add_u64 v[64:65], v[100:101], 0, s[30:31]
	s_nop 0
	v_addc_co_u32_e32 v45, vcc, 0, v61, vcc
	v_add_co_u32_e32 v48, vcc, 0xc000, v56
	v_lshl_add_u64 v[66:67], v[102:103], 0, s[30:31]
	s_nop 0
	v_addc_co_u32_e32 v49, vcc, 0, v57, vcc
	v_add_co_u32_e32 v52, vcc, 0xc00000, v60
	flat_load_dwordx4 v[8:11], v[8:9]
	s_nop 0
	v_addc_co_u32_e32 v53, vcc, 0, v61, vcc
	v_add_co_u32_e32 v56, vcc, 0xe000, v56
	flat_load_dwordx4 v[12:15], v[12:13]
	s_nop 0
	v_addc_co_u32_e32 v57, vcc, 0, v57, vcc
	v_add_co_u32_e32 v60, vcc, 0xe00000, v60
	flat_load_dwordx4 v[16:19], v[16:17]
	s_nop 0
	v_addc_co_u32_e32 v61, vcc, 0, v61, vcc
	flat_load_dwordx4 v[20:23], v[20:21]
	s_nop 0
	flat_load_dwordx4 v[24:27], v[24:25]
	s_nop 0
	flat_load_dwordx4 v[28:31], v[28:29]
	s_nop 0
	flat_load_dwordx4 v[32:35], v[32:33]
	s_nop 0
	flat_load_dwordx4 v[36:39], v[36:37]
	s_nop 0
	flat_load_dwordx4 v[40:43], v[40:41]
	s_nop 0
	flat_load_dwordx4 v[44:47], v[44:45]
	s_nop 0
	flat_load_dwordx4 v[48:51], v[48:49]
	s_nop 0
	flat_load_dwordx4 v[52:55], v[52:53]
	s_nop 0
	flat_load_dwordx4 v[56:59], v[56:57]
	s_nop 0
	flat_load_dwordx4 v[60:63], v[60:61]
	s_nop 0
	flat_load_dword v176, v[64:65]
	flat_load_dword v178, v[64:65] offset:128
	flat_load_dword v180, v[64:65] offset:256
	flat_load_dword v181, v[64:65] offset:384
	flat_load_dword v182, v[64:65] offset:512
	flat_load_dword v183, v[64:65] offset:640
	flat_load_dword v184, v[64:65] offset:768
	flat_load_dword v185, v[64:65] offset:896
	flat_load_dword v186, v[66:67]
	flat_load_dword v187, v[66:67] offset:128
	flat_load_dword v188, v[66:67] offset:256
	flat_load_dword v190, v[66:67] offset:384
	flat_load_dword v191, v[66:67] offset:512
	flat_load_dword v192, v[66:67] offset:640
	flat_load_dword v194, v[66:67] offset:768
	flat_load_dword v195, v[66:67] offset:896
	s_branch .LBB0_130
; __device__ __forceinline__ void sgu_phase(LAS unsigned char* lds, const bf16_t* U, const bf16_t* VTg, const float* vg, const float* vb, const float* wsp, const float* bsp, bf16_t* Gout, int bid, int G, const int tid) {
;     ...
;                 u32x2 ureg[8];
;                 const int t = 16 * w + fr;
;                 const unsigned voffU = (unsigned)((t * D + fq * 4) * 2);
;                 const char* bu = (const char*)(U + r0 * D + g * 256 + hf * 128); char* bg = (char*)(Gout + r0 * D + g * 256 + hf * 128);
; #pragma unroll
;                 for (int d = 0; d < 8; ++d) ureg[d] = *(const u32x2*)(bu + voffU + d * 32);
;     ...
;                 const float bias = bsp[g * 128 + t];
.Lsgu_last:
	v_lshl_add_u32 v64, s15, 7, v155
	s_lshl_b32 s26, s15, 9
	v_ashrrev_i32_e32 v65, 31, v64
	v_lshl_add_u64 v[130:131], v[126:127], 0, s[26:27]
	v_lshl_add_u64 v[132:133], v[64:65], 2, s[38:39]
	global_load_dwordx2 v[150:151], v[130:131], off
	global_load_dwordx2 v[148:149], v[130:131], off offset:32
	global_load_dwordx2 v[146:147], v[130:131], off offset:64
	global_load_dwordx2 v[144:145], v[130:131], off offset:96
	global_load_dwordx2 v[142:143], v[130:131], off offset:128
	global_load_dwordx2 v[140:141], v[130:131], off offset:160
	global_load_dwordx2 v[138:139], v[130:131], off offset:192
	global_load_dwordx2 v[136:137], v[130:131], off offset:224
	global_load_dwordx2 v[210:211], v[130:131], off offset:256
	global_load_dwordx2 v[212:213], v[130:131], off offset:288
	global_load_dwordx2 v[214:215], v[130:131], off offset:320
	global_load_dwordx2 v[216:217], v[130:131], off offset:352
	global_load_dwordx2 v[218:219], v[130:131], off offset:384
	global_load_dwordx2 v[220:221], v[130:131], off offset:416
	global_load_dwordx2 v[222:223], v[130:131], off offset:448
	global_load_dwordx2 v[224:225], v[130:131], off offset:480
	global_load_dword v252, v[132:133], off

; __device__ __forceinline__ void sgu_phase(LAS unsigned char* lds, const bf16_t* U, const bf16_t* VTg, const float* vg, const float* vb, const float* wsp, const float* bsp, bf16_t* Gout, int bid, int G, const int tid) {
;     ...
;                 const float bias = bsp[g * 128 + t];
; #pragma unroll
;                 for (int d = 0; d < 8; ++d) {
;                     const u32x2 uu = ureg[d];
.LBB0_131:
	s_cmp_eq_u64 s[30:31], 0
	s_cbranch_scc1 .Lsgu_w1
	s_cmp_eq_u32 s3, 8
	s_cbranch_scc1 .Lsgu_w0
	s_waitcnt vmcnt(32)
	s_branch .Lsgu_w1

; __device__ __forceinline__ unsigned cvt_pk_bf16(float lo, float hi) { unsigned r; asm("v_cvt_pk_bf16_f32 %0, %1, %2" : "=v"(r) : "v"(lo), "v"(hi)); return r; }
; __device__ __forceinline__ float bf_lo(unsigned u) { return __uint_as_float(u << 16); }
; __device__ __forceinline__ float bf_hi(unsigned u) { return __uint_as_float(u & 0xffff0000u); }
; __device__ __forceinline__ void sgu_phase(LAS unsigned char* lds, const bf16_t* U, const bf16_t* VTg, const float* vg, const float* vb, const float* wsp, const float* bsp, bf16_t* Gout, int bid, int G, const int tid) {
;     ...
;             for (int hf = 0; hf < 2; ++hf) {
;                 u32x2 ureg[8];
;                 const int t = 16 * w + fr;
;                 const unsigned voffU = (unsigned)((t * D + fq * 4) * 2);
;                 const char* bu = (const char*)(U + r0 * D + g * 256 + hf * 128); char* bg = (char*)(Gout + r0 * D + g * 256 + hf * 128);
; #pragma unroll
;                 for (int d = 0; d < 8; ++d) ureg[d] = *(const u32x2*)(bu + voffU + d * 32);
;                 f32x4 acc[8];
; #pragma unroll
;                 for (int d = 0; d < 8; ++d) acc[d] = (f32x4){0.f, 0.f, 0.f, 0.f};
;     ...
;                 const float bias = bsp[g * 128 + t];
; #pragma unroll
;                 for (int d = 0; d < 8; ++d) {
;                     const u32x2 uu = ureg[d];
;                     u32x2 o; o.x = cvt_pk_bf16(bf_lo(uu.x) * (acc[d][0] + bias), bf_hi(uu.x) * (acc[d][1] + bias));
;                     o.y = cvt_pk_bf16(bf_lo(uu.y) * (acc[d][2] + bias), bf_hi(uu.y) * (acc[d][3] + bias));
;                     *(u32x2*)(bg + voffU + d * 32) = o;
;                 }
.Lsgu_w1:
	s_waitcnt lgkmcnt(0)
	v_mov_b32_e32 v198, v252
	v_lshlrev_b32_e32 v199, 16, v150
	v_and_b32_e32 v150, 0xffff0000, v150
	v_lshlrev_b32_e32 v200, 16, v151
	v_and_b32_e32 v151, 0xffff0000, v151
	v_lshlrev_b32_e32 v203, 16, v146
	v_and_b32_e32 v146, 0xffff0000, v146
	v_lshlrev_b32_e32 v205, 16, v144
	v_and_b32_e32 v144, 0xffff0000, v144
	v_lshlrev_b32_e32 v206, 16, v145
	v_and_b32_e32 v145, 0xffff0000, v145
	v_lshlrev_b32_e32 v209, 16, v140
	v_and_b32_e32 v140, 0xffff0000, v140
	v_lshl_add_u64 v[196:197], s[26:27], 1, v[134:135]
	v_lshlrev_b32_e32 v201, 16, v148
	v_and_b32_e32 v148, 0xffff0000, v148
	v_lshlrev_b32_e32 v202, 16, v149
	v_and_b32_e32 v149, 0xffff0000, v149
	v_lshlrev_b32_e32 v204, 16, v147
	v_and_b32_e32 v147, 0xffff0000, v147
	v_lshlrev_b32_e32 v207, 16, v142
	v_and_b32_e32 v142, 0xffff0000, v142
	v_lshlrev_b32_e32 v208, 16, v143
	v_and_b32_e32 v143, 0xffff0000, v143
	s_xor_b64 vcc, s[30:31], -1
	s_movk_i32 s26, 0x80
	s_mov_b64 s[30:31], 0
	s_and_b64 vcc, exec, vcc
	v_add_f32_e32 v92, v198, v92
	v_add_f32_e32 v93, v198, v93
	v_add_f32_e32 v94, v198, v94
	v_add_f32_e32 v95, v198, v95
	v_add_f32_e32 v85, v85, v198
	v_add_f32_e32 v80, v80, v198
	v_add_f32_e32 v81, v81, v198
	v_add_f32_e32 v82, v82, v198
	v_add_f32_e32 v83, v83, v198
	v_add_f32_e32 v72, v72, v198
	v_add_f32_e32 v73, v73, v198
	v_add_f32_e32 v88, v88, v198
	v_add_f32_e32 v89, v89, v198
	v_add_f32_e32 v90, v90, v198
	v_add_f32_e32 v91, v91, v198
	v_add_f32_e32 v84, v84, v198
	v_add_f32_e32 v86, v86, v198
	v_add_f32_e32 v87, v87, v198
	v_add_f32_e32 v76, v76, v198
	v_add_f32_e32 v77, v77, v198
	v_add_f32_e32 v78, v78, v198
	v_add_f32_e32 v79, v79, v198
	v_mul_f32_e32 v92, v92, v199
	v_mul_f32_e32 v93, v93, v150
	v_mul_f32_e32 v94, v94, v200
	v_mul_f32_e32 v95, v95, v151
	v_mul_f32_e32 v85, v85, v146
	v_mul_f32_e32 v80, v80, v205
	v_mul_f32_e32 v81, v81, v144
	v_mul_f32_e32 v82, v82, v206
	v_mul_f32_e32 v83, v83, v145
	v_mul_f32_e32 v146, v72, v209
	v_mul_f32_e32 v140, v73, v140
	v_cvt_pk_bf16_f32 v72, v92, v93
	v_cvt_pk_bf16_f32 v73, v94, v95
	v_mul_f32_e32 v88, v88, v201
	v_mul_f32_e32 v89, v89, v148
	v_mul_f32_e32 v90, v90, v202
	v_mul_f32_e32 v91, v91, v149
	v_mul_f32_e32 v84, v84, v203
	v_mul_f32_e32 v86, v86, v204
	v_mul_f32_e32 v87, v87, v147
	v_mul_f32_e32 v144, v76, v207
	v_mul_f32_e32 v142, v77, v142
	v_mul_f32_e32 v145, v78, v208
	v_mul_f32_e32 v143, v79, v143
	v_cvt_pk_bf16_f32 v76, v88, v89
	v_cvt_pk_bf16_f32 v77, v90, v91
	v_cvt_pk_bf16_f32 v78, v84, v85
	v_cvt_pk_bf16_f32 v79, v86, v87
	v_cvt_pk_bf16_f32 v80, v80, v81
	v_cvt_pk_bf16_f32 v81, v82, v83
	v_cvt_pk_bf16_f32 v82, v144, v142
	v_cvt_pk_bf16_f32 v83, v145, v143
	flat_store_dwordx2 v[196:197], v[72:73]
	flat_store_dwordx2 v[196:197], v[76:77] offset:32
	flat_store_dwordx2 v[196:197], v[78:79] offset:64
	flat_store_dwordx2 v[196:197], v[80:81] offset:96
	flat_store_dwordx2 v[196:197], v[82:83] offset:128
	v_lshlrev_b32_e32 v72, 16, v141
	v_add_f32_e32 v73, v74, v198
	v_mul_f32_e32 v72, v73, v72
	v_and_b32_e32 v73, 0xffff0000, v141
	v_add_f32_e32 v74, v75, v198
	v_mul_f32_e32 v73, v74, v73
	v_cvt_pk_bf16_f32 v85, v72, v73
	v_lshlrev_b32_e32 v72, 16, v138
	v_add_f32_e32 v68, v68, v198
	v_mul_f32_e32 v68, v68, v72
	v_and_b32_e32 v72, 0xffff0000, v138
	v_add_f32_e32 v69, v69, v198
	v_mul_f32_e32 v69, v69, v72
	v_cvt_pk_bf16_f32 v68, v68, v69
	v_lshlrev_b32_e32 v69, 16, v139
	v_add_f32_e32 v70, v70, v198
	v_mul_f32_e32 v69, v70, v69
	v_and_b32_e32 v70, 0xffff0000, v139
	v_add_f32_e32 v71, v71, v198
	v_mul_f32_e32 v70, v71, v70
	v_cvt_pk_bf16_f32 v69, v69, v70
	flat_store_dwordx2 v[196:197], v[68:69] offset:192
	v_lshlrev_b32_e32 v68, 16, v136
	v_add_f32_e32 v64, v64, v198
	v_mul_f32_e32 v64, v64, v68
	v_and_b32_e32 v68, 0xffff0000, v136
	v_add_f32_e32 v65, v65, v198
	v_mul_f32_e32 v65, v65, v68
	v_cvt_pk_bf16_f32 v64, v64, v65
	v_lshlrev_b32_e32 v65, 16, v137
	v_add_f32_e32 v66, v66, v198
	v_mul_f32_e32 v65, v66, v65
	v_and_b32_e32 v66, 0xffff0000, v137
	v_add_f32_e32 v67, v67, v198
	v_cvt_pk_bf16_f32 v84, v146, v140
	flat_store_dwordx2 v[196:197], v[84:85] offset:160
	v_mul_f32_e32 v66, v67, v66
	v_cvt_pk_bf16_f32 v65, v65, v66
	flat_store_dwordx2 v[196:197], v[64:65] offset:224
	s_cbranch_vccnz .LBB0_127
.LBB0_132:
	v_lshl_add_u64 v[64:65], s[26:27], 1, v[130:131]
	s_cmp_eq_u32 s26, 0
	s_cbranch_scc1 .Lsgu_hf0
	v_mov_b32_e32 v150, v210
	v_mov_b32_e32 v151, v211
	v_mov_b32_e32 v148, v212
	v_mov_b32_e32 v149, v213
	v_mov_b32_e32 v146, v214
	v_mov_b32_e32 v147, v215
	v_mov_b32_e32 v144, v216
	v_mov_b32_e32 v145, v217
	v_mov_b32_e32 v142, v218
	v_mov_b32_e32 v143, v219
	v_mov_b32_e32 v140, v220
	v_mov_b32_e32 v141, v221
	v_mov_b32_e32 v138, v222
	v_mov_b32_e32 v139, v223
	v_mov_b32_e32 v136, v224
	v_mov_b32_e32 v137, v225
.Lsgu_hf0:
	v_mov_b32_e32 v95, 0
	s_andn2_b64 vcc, exec, s[20:21]
	v_mov_b32_e32 v94, v95
	v_mov_b32_e32 v93, v95
	v_mov_b32_e32 v92, v95
	v_mov_b32_e32 v91, v95
	v_mov_b32_e32 v90, v95
	v_mov_b32_e32 v89, v95
	v_mov_b32_e32 v88, v95
	v_mov_b32_e32 v87, v95
	v_mov_b32_e32 v86, v95
	v_mov_b32_e32 v85, v95
	v_mov_b32_e32 v84, v95
	v_mov_b32_e32 v83, v95
	v_mov_b32_e32 v82, v95
	v_mov_b32_e32 v81, v95
	v_mov_b32_e32 v80, v95
	v_mov_b32_e32 v79, v95
	v_mov_b32_e32 v78, v95
	v_mov_b32_e32 v77, v95
	v_mov_b32_e32 v76, v95
	v_mov_b32_e32 v75, v95
	v_mov_b32_e32 v74, v95
	v_mov_b32_e32 v73, v95
	v_mov_b32_e32 v72, v95
	v_mov_b32_e32 v71, v95
	v_mov_b32_e32 v70, v95
	v_mov_b32_e32 v69, v95
	v_mov_b32_e32 v68, v95
	v_mov_b32_e32 v67, v95
	v_mov_b32_e32 v66, v95
	v_mov_b32_e32 v65, v95
	v_mov_b32_e32 v64, v95
	s_cbranch_vccnz .LBB0_131
	v_or_b32_e32 v64, s26, v152
	v_mad_u32_u24 v196, v64, s37, v157
	v_mov_b32_e32 v64, 0
	v_mov_b32_e32 v197, v158
	s_mov_b32 s15, s13
	v_mov_b32_e32 v65, v64
	v_mov_b32_e32 v66, v64
	v_mov_b32_e32 v67, v64
	v_mov_b32_e32 v68, v64
	v_mov_b32_e32 v69, v64
	v_mov_b32_e32 v70, v64
	v_mov_b32_e32 v71, v64
	v_mov_b32_e32 v72, v64
	v_mov_b32_e32 v73, v64
	v_mov_b32_e32 v74, v64
	v_mov_b32_e32 v75, v64
	v_mov_b32_e32 v76, v64
	v_mov_b32_e32 v77, v64
	v_mov_b32_e32 v78, v64
	v_mov_b32_e32 v79, v64
	v_mov_b32_e32 v80, v64
	v_mov_b32_e32 v81, v64
	v_mov_b32_e32 v82, v64
	v_mov_b32_e32 v83, v64
	v_mov_b32_e32 v84, v64
	v_mov_b32_e32 v85, v64
	v_mov_b32_e32 v86, v64
	v_mov_b32_e32 v87, v64
	v_mov_b32_e32 v88, v64
	v_mov_b32_e32 v89, v64
	v_mov_b32_e32 v90, v64
	v_mov_b32_e32 v91, v64
	v_mov_b32_e32 v92, v64
	v_mov_b32_e32 v93, v64
	v_mov_b32_e32 v94, v64
	v_mov_b32_e32 v95, v64

; #define LAS __attribute__((address_space(3)))
; __device__ __forceinline__ void conv_phase(LAS unsigned char* lds, const bf16_t* P, const float* cw, const float* cb, const float* ng, const float* nb, bf16_t* CAT, int bid, int G, const int tid) {
;     LAS float* zs = (LAS float*)lds;
;     LAS float* co = (LAS float*)(lds + 94 * 128 * 4);
;     const int lane = tid & 63, w = tid >> 6;
;     u32x4 ra[3], rg[3];
;     ...
;     if (bid < 4096) CONV_LOAD(bid);
.LBB0_161:
	s_load_dwordx2 s[4:5], s[0:1], 0x98
	s_waitcnt lgkmcnt(0)
	s_load_dwordx2 s[6:7], s[0:1], 0xa0
	s_waitcnt lgkmcnt(0)
	s_load_dwordx2 s[20:21], s[0:1], 0xa8
	s_waitcnt lgkmcnt(0)
	s_load_dwordx2 s[30:31], s[0:1], 0xb0
	s_waitcnt lgkmcnt(0)
	s_cmpk_gt_i32 s12, 0xfff
	s_cbranch_scc1 .LBB0_186
	s_mov_b32 s63, -1
	s_and_b32 s3, s50, 0x7c0
	s_lshl_b32 s15, s12, 8
	s_sub_i32 s13, s3, 30
	s_and_b32 s3, s50, 0xfffff800
	s_and_b32 s15, s15, 0x700
	v_lshlrev_b32_e32 v30, 3, v238
	v_ashrrev_i32_e32 v36, 4, v238
	s_add_u32 s34, s10, s15
	v_and_b32_e32 v26, 0x78, v30
	v_add_u32_e32 v5, s13, v36
	s_movk_i32 s15, 0x5e0
	v_mov_b32_e32 v2, v177
	v_mov_b32_e32 v3, v177
	s_addc_u32 s35, s11, 0
	v_lshlrev_b32_e32 v176, 1, v26
	v_cmp_gt_i32_e64 s[38:39], s15, v238
	v_cmp_lt_i32_e32 vcc, -1, v5
	v_mov_b32_e32 v0, v177
	v_mov_b32_e32 v1, v177
	v_mov_b64_e32 v[14:15], v[2:3]
	v_lshl_add_u64 v[24:25], s[34:35], 0, v[176:177]
	s_and_b64 s[40:41], s[38:39], vcc
	v_mov_b32_e32 v4, 0
	v_mov_b64_e32 v[12:13], v[0:1]
	v_mov_b32_e32 v8, 0
	v_mov_b32_e32 v9, 0
	v_mov_b32_e32 v10, 0
	v_mov_b32_e32 v11, 0
	s_and_saveexec_b64 s[34:35], s[40:41]
	s_cbranch_execz .LBB0_164
	v_add_u32_e32 v5, s3, v5
	v_mad_i64_i32 v[6:7], s[40:41], v5, s48, v[24:25]
	v_add_co_u32_e32 v12, vcc, 0x1000, v6
	s_nop 1
	v_addc_co_u32_e32 v13, vcc, 0, v7, vcc
	global_load_dwordx4 v[8:11], v[6:7], off offset:2176
	s_nop 0
	global_load_dwordx4 v[12:15], v[12:13], off offset:128
.LBB0_164:
	s_or_b64 exec, exec, s[34:35]
	v_add_u32_e32 v31, 0x200, v238
	v_ashrrev_i32_e32 v37, 4, v31
	v_add_u32_e32 v16, s13, v37
	s_movk_i32 s15, 0x3e0
	v_cmp_gt_i32_e64 s[40:41], s15, v238
	v_cmp_lt_i32_e32 vcc, -1, v16
	s_and_b64 s[42:43], s[40:41], vcc
	v_mov_b32_e32 v5, 0
	v_mov_b32_e32 v6, 0
	v_mov_b32_e32 v7, 0
	s_and_saveexec_b64 s[34:35], s[42:43]
	s_cbranch_execz .LBB0_166
	v_add_u32_e32 v0, s3, v16
	v_mad_i64_i32 v[0:1], s[42:43], v0, s48, v[24:25]
	v_add_co_u32_e32 v2, vcc, 0x1000, v0
	s_nop 1
	v_addc_co_u32_e32 v3, vcc, 0, v1, vcc
	global_load_dwordx4 v[4:7], v[0:1], off offset:2176
	s_nop 0
	global_load_dwordx4 v[0:3], v[2:3], off offset:128
.LBB0_166:
	s_or_b64 exec, exec, s[34:35]
	v_add_u32_e32 v32, 0x400, v238
	v_ashrrev_i32_e32 v38, 4, v32
	v_add_u32_e32 v27, s13, v38
	s_movk_i32 s13, 0x1e0
	v_cmp_gt_i32_e64 s[42:43], s13, v238
	v_cmp_lt_i32_e32 vcc, -1, v27
	s_and_b64 s[44:45], s[42:43], vcc
	v_mov_b32_e32 v20, 0
	v_mov_b32_e32 v21, 0
	v_mov_b32_e32 v22, 0
	v_mov_b32_e32 v23, 0
	v_mov_b32_e32 v16, 0
	v_mov_b32_e32 v17, 0
	v_mov_b32_e32 v18, 0
	v_mov_b32_e32 v19, 0
	s_and_saveexec_b64 s[34:35], s[44:45]
	s_cbranch_execz .LBB0_168
	v_add_u32_e32 v16, s3, v27
	v_mad_i64_i32 v[16:17], s[44:45], v16, s48, v[24:25]
	v_add_co_u32_e32 v20, vcc, 0x1000, v16
	s_nop 1
	v_addc_co_u32_e32 v21, vcc, 0, v17, vcc
	global_load_dwordx4 v[16:19], v[16:17], off offset:2176
	s_nop 0
	global_load_dwordx4 v[20:23], v[20:21], off offset:128

; __device__ __forceinline__ void conv_phase(LAS unsigned char* lds, const bf16_t* P, const float* cw, const float* cb, const float* ng, const float* nb, bf16_t* CAT, int bid, int G, const int tid) {
;     ...
;             float wj[31];
; #pragma unroll
;             for (int j = 0; j < 31; ++j) wj[j] = cw[j * 1024 + g * 128 + c];
;             const float bias = cb[g * 128 + c];
.LBB0_170:
	s_and_b32 s30, s35, 0x380
	s_cmp_eq_u32 s30, s63
	s_cbranch_scc1 .Lconv_wok
	s_mov_b32 s63, s30
	v_or_b32_e32 v226, s30, v39
	v_lshlrev_b32_e32 v226, 2, v226
	s_mov_b64 s[64:65], s[4:5]
	global_load_dword v194, v226, s[64:65]
	s_add_u32 s64, s64, 0x1000
	s_addc_u32 s65, s65, 0
	global_load_dword v195, v226, s[64:65]
	s_add_u32 s64, s64, 0x1000
	s_addc_u32 s65, s65, 0
	global_load_dword v196, v226, s[64:65]
	s_add_u32 s64, s64, 0x1000
	s_addc_u32 s65, s65, 0
	global_load_dword v197, v226, s[64:65]
	s_add_u32 s64, s64, 0x1000
	s_addc_u32 s65, s65, 0
	global_load_dword v198, v226, s[64:65]
	s_add_u32 s64, s64, 0x1000
	s_addc_u32 s65, s65, 0
	global_load_dword v199, v226, s[64:65]
	s_add_u32 s64, s64, 0x1000
	s_addc_u32 s65, s65, 0
	global_load_dword v200, v226, s[64:65]
	s_add_u32 s64, s64, 0x1000
	s_addc_u32 s65, s65, 0
	global_load_dword v201, v226, s[64:65]
	s_add_u32 s64, s64, 0x1000
	s_addc_u32 s65, s65, 0
	global_load_dword v202, v226, s[64:65]
	s_add_u32 s64, s64, 0x1000
	s_addc_u32 s65, s65, 0
	global_load_dword v203, v226, s[64:65]
	s_add_u32 s64, s64, 0x1000
	s_addc_u32 s65, s65, 0
	global_load_dword v204, v226, s[64:65]
	s_add_u32 s64, s64, 0x1000
	s_addc_u32 s65, s65, 0
	global_load_dword v205, v226, s[64:65]
	s_add_u32 s64, s64, 0x1000
	s_addc_u32 s65, s65, 0
	global_load_dword v206, v226, s[64:65]
	s_add_u32 s64, s64, 0x1000
	s_addc_u32 s65, s65, 0
	global_load_dword v207, v226, s[64:65]
	s_add_u32 s64, s64, 0x1000
	s_addc_u32 s65, s65, 0
	global_load_dword v208, v226, s[64:65]
	s_add_u32 s64, s64, 0x1000
	s_addc_u32 s65, s65, 0
	global_load_dword v209, v226, s[64:65]
	s_add_u32 s64, s64, 0x1000
	s_addc_u32 s65, s65, 0
	global_load_dword v210, v226, s[64:65]
	s_add_u32 s64, s64, 0x1000
	s_addc_u32 s65, s65, 0
	global_load_dword v211, v226, s[64:65]
	s_add_u32 s64, s64, 0x1000
	s_addc_u32 s65, s65, 0
	global_load_dword v212, v226, s[64:65]
	s_add_u32 s64, s64, 0x1000
	s_addc_u32 s65, s65, 0
	global_load_dword v213, v226, s[64:65]
	s_add_u32 s64, s64, 0x1000
	s_addc_u32 s65, s65, 0
	global_load_dword v214, v226, s[64:65]
	s_add_u32 s64, s64, 0x1000
	s_addc_u32 s65, s65, 0
	global_load_dword v215, v226, s[64:65]
	s_add_u32 s64, s64, 0x1000
	s_addc_u32 s65, s65, 0
	global_load_dword v216, v226, s[64:65]
	s_add_u32 s64, s64, 0x1000
	s_addc_u32 s65, s65, 0
	global_load_dword v217, v226, s[64:65]
	s_add_u32 s64, s64, 0x1000
	s_addc_u32 s65, s65, 0
	global_load_dword v218, v226, s[64:65]
	s_add_u32 s64, s64, 0x1000
	s_addc_u32 s65, s65, 0
	global_load_dword v219, v226, s[64:65]
	s_add_u32 s64, s64, 0x1000
	s_addc_u32 s65, s65, 0
	global_load_dword v220, v226, s[64:65]
	s_add_u32 s64, s64, 0x1000
	s_addc_u32 s65, s65, 0
	global_load_dword v221, v226, s[64:65]
	s_add_u32 s64, s64, 0x1000
	s_addc_u32 s65, s65, 0
	global_load_dword v222, v226, s[64:65]
	s_add_u32 s64, s64, 0x1000
	s_addc_u32 s65, s65, 0
	global_load_dword v223, v226, s[64:65]
	s_add_u32 s64, s64, 0x1000
	s_addc_u32 s65, s65, 0
	global_load_dword v224, v226, s[64:65]
	global_load_dword v225, v226, s[6:7]
	s_waitcnt vmcnt(0)
.Lconv_wok:
	v_or_b32_e32 v31, s30, v39
	v_lshlrev_b32_e32 v176, 2, v31
	v_lshl_add_u64 v[32:33], s[4:5], 0, v[176:177]
	v_add_co_u32_e32 v34, vcc, 0x1000, v32
	v_mov_b32_e32 v107, v194
	s_nop 0
	v_addc_co_u32_e32 v35, vcc, 0, v33, vcc
	v_mov_b32_e32 v105, v195
	v_add_co_u32_e32 v34, vcc, 0x2000, v32
	s_mov_b32 s26, 0xa000
	s_nop 0
	v_addc_co_u32_e32 v35, vcc, 0, v33, vcc
	v_mov_b32_e32 v104, v196
	v_add_co_u32_e32 v34, vcc, 0x3000, v32
	v_lshl_add_u64 v[86:87], s[6:7], 0, v[176:177]
	s_nop 0
	v_addc_co_u32_e32 v35, vcc, 0, v33, vcc
	v_mov_b32_e32 v101, v197
	v_add_co_u32_e32 v34, vcc, 0x4000, v32
	ds_read2st64_b32 v[90:91], v40 offset0:12 offset1:14
	s_nop 0
	v_addc_co_u32_e32 v35, vcc, 0, v33, vcc
	v_mov_b32_e32 v100, v198
	v_add_co_u32_e32 v34, vcc, 0x5000, v32
	ds_read2st64_b32 v[94:95], v40 offset0:16 offset1:18
	s_nop 0
	v_addc_co_u32_e32 v35, vcc, 0, v33, vcc
	v_mov_b32_e32 v97, v199
	v_add_co_u32_e32 v34, vcc, 0x6000, v32
	ds_read2st64_b32 v[98:99], v40 offset0:20 offset1:22
	s_nop 0
	v_addc_co_u32_e32 v35, vcc, 0, v33, vcc
	v_mov_b32_e32 v96, v200
	v_add_co_u32_e32 v34, vcc, 0x7000, v32
	ds_read2st64_b32 v[102:103], v40 offset0:24 offset1:26
	s_nop 0
	v_addc_co_u32_e32 v35, vcc, 0, v33, vcc
	v_mov_b32_e32 v93, v201
	v_add_co_u32_e32 v34, vcc, s72, v32
	ds_read2st64_b32 v[108:109], v40 offset0:28 offset1:30
	s_nop 0
	v_addc_co_u32_e32 v35, vcc, 0, v33, vcc
	v_mov_b32_e32 v92, v202
	v_add_co_u32_e32 v34, vcc, 0x9000, v32
	s_and_b32 s31, s34, 0xffffffc0
	s_nop 0
	v_addc_co_u32_e32 v35, vcc, 0, v33, vcc
	v_mov_b32_e32 v89, v203
	v_add_co_u32_e32 v34, vcc, s26, v32
	s_mov_b32 s26, 0xe000
	s_nop 0
	v_addc_co_u32_e32 v35, vcc, 0, v33, vcc
	v_mov_b32_e32 v88, v204
	v_add_co_u32_e32 v34, vcc, 0xb000, v32
	s_mov_b32 s34, s15
	s_nop 0
	v_addc_co_u32_e32 v35, vcc, 0, v33, vcc
	v_mov_b32_e32 v85, v205
	v_add_co_u32_e32 v34, vcc, s73, v32
	s_mov_b32 s35, s17
	s_nop 0
	v_addc_co_u32_e32 v35, vcc, 0, v33, vcc
	v_mov_b32_e32 v82, v206
	v_add_co_u32_e32 v34, vcc, 0xd000, v32
	s_nop 1
	v_addc_co_u32_e32 v35, vcc, 0, v33, vcc
	v_mov_b32_e32 v81, v207
	v_add_co_u32_e32 v34, vcc, s26, v32
	s_mov_b32 s26, 0xf000
	s_nop 0
	v_addc_co_u32_e32 v35, vcc, 0, v33, vcc
	v_mov_b32_e32 v80, v208
	v_add_co_u32_e32 v34, vcc, s26, v32
	s_mov_b32 s26, 0x10000
	s_nop 0
	v_addc_co_u32_e32 v35, vcc, 0, v33, vcc
	v_mov_b32_e32 v79, v209
	v_add_co_u32_e32 v34, vcc, s26, v32
	s_mov_b32 s26, 0x11000
	s_nop 0
	v_addc_co_u32_e32 v35, vcc, 0, v33, vcc
	v_mov_b32_e32 v78, v210
	v_add_co_u32_e32 v34, vcc, s26, v32
	s_mov_b32 s26, 0x12000
	s_nop 0
	v_addc_co_u32_e32 v35, vcc, 0, v33, vcc
; __device__ __forceinline__ void conv_phase(LAS unsigned char* lds, const bf16_t* P, const float* cw, const float* cb, const float* ng, const float* nb, bf16_t* CAT, int bid, int G, const int tid) {
;     ...
;             for (int j = 0; j < 31; ++j) wj[j] = cw[j * 1024 + g * 128 + c];
;             const float bias = cb[g * 128 + c];
;             float acc[16];
; #pragma unroll
;             for (int o = 0; o < 16; ++o) acc[o] = bias;
; #pragma unroll
;             for (int i = 0; i < 46; ++i) {
;                 const float z = zs[(tb * 16 + i) * 128 + c];
; #pragma unroll
;                 for (int o = 0; o < 16; ++o) { const int j = i - o; if (j >= 0 && j <= 30) acc[o] += wj[j] * z; }
	v_mov_b32_e32 v77, v211
	v_add_co_u32_e32 v34, vcc, s26, v32
	s_mov_b32 s26, 0x13000
	s_nop 0
	v_addc_co_u32_e32 v35, vcc, 0, v33, vcc
	v_mov_b32_e32 v76, v212
	v_add_co_u32_e32 v34, vcc, s26, v32
	s_mov_b32 s26, 0x14000
	s_nop 0
	v_addc_co_u32_e32 v35, vcc, 0, v33, vcc
	v_mov_b32_e32 v73, v213
	v_add_co_u32_e32 v34, vcc, s26, v32
	s_mov_b32 s26, 0x15000
	s_nop 0
	v_addc_co_u32_e32 v35, vcc, 0, v33, vcc
	v_mov_b32_e32 v72, v214
	v_add_co_u32_e32 v34, vcc, s26, v32
	s_mov_b32 s26, 0x16000
	s_nop 0
	v_addc_co_u32_e32 v35, vcc, 0, v33, vcc
	v_mov_b32_e32 v71, v215
	v_add_co_u32_e32 v34, vcc, s26, v32
	s_mov_b32 s26, 0x17000
	s_nop 0
	v_addc_co_u32_e32 v35, vcc, 0, v33, vcc
	v_mov_b32_e32 v70, v216
	v_add_co_u32_e32 v34, vcc, s26, v32
	s_mov_b32 s26, 0x18000
	s_nop 0
	v_addc_co_u32_e32 v35, vcc, 0, v33, vcc
	v_mov_b32_e32 v69, v217
	v_add_co_u32_e32 v34, vcc, s26, v32
	s_mov_b32 s26, 0x19000
	s_nop 0
	v_addc_co_u32_e32 v35, vcc, 0, v33, vcc
	v_mov_b32_e32 v68, v218
	v_add_co_u32_e32 v34, vcc, s26, v32
	s_mov_b32 s26, 0x1a000
	s_nop 0
	v_addc_co_u32_e32 v35, vcc, 0, v33, vcc
	v_mov_b32_e32 v67, v219
	v_add_co_u32_e32 v34, vcc, s26, v32
	s_mov_b32 s26, 0x1b000
	s_nop 0
	v_addc_co_u32_e32 v35, vcc, 0, v33, vcc
	v_mov_b32_e32 v66, v220
	v_add_co_u32_e32 v34, vcc, s26, v32
	s_mov_b32 s26, 0x1c000
	s_nop 0
	v_addc_co_u32_e32 v35, vcc, 0, v33, vcc
	v_add_co_u32_e32 v74, vcc, s26, v32
	s_mov_b32 s26, 0x1d000
	s_nop 0
	v_addc_co_u32_e32 v75, vcc, 0, v33, vcc
	v_mov_b32_e32 v34, v221
	s_nop 0
	v_mov_b32_e32 v35, v222
	v_add_co_u32_e32 v74, vcc, s26, v32
	s_mov_b32 s26, 0x1e000
	s_nop 0
	v_addc_co_u32_e32 v75, vcc, 0, v33, vcc
	v_add_co_u32_e32 v32, vcc, s26, v32
	v_mov_b32_e32 v31, v223
	s_nop 0
	v_addc_co_u32_e32 v33, vcc, 0, v33, vcc
	v_mov_b32_e32 v32, v224
	ds_read2st64_b32 v[74:75], v40 offset1:2
	v_mov_b32_e32 v33, v225
	ds_read2st64_b32 v[86:87], v40 offset0:4 offset1:6
	s_lshl_b32 s26, s30, 2
	s_andn2_b64 vcc, exec, s[20:21]
	s_waitcnt lgkmcnt(0)
	v_fma_f32 v74, v107, v74, v33
	v_fmac_f32_e32 v74, v105, v75
	v_fma_f32 v75, v107, v75, v33
	v_fmac_f32_e32 v74, v104, v86
	v_fmac_f32_e32 v75, v105, v86
	v_fma_f32 v83, v107, v86, v33
	v_fmac_f32_e32 v74, v101, v87
	v_fmac_f32_e32 v75, v104, v87
	v_fmac_f32_e32 v83, v105, v87
	v_fma_f32 v84, v107, v87, v33
	ds_read2st64_b32 v[86:87], v40 offset0:8 offset1:10
	v_fma_f32 v106, v107, v108, v33
	v_fmac_f32_e32 v106, v105, v109
	s_waitcnt lgkmcnt(0)
	v_fmac_f32_e32 v74, v100, v86
	v_fmac_f32_e32 v75, v101, v86
	v_fmac_f32_e32 v83, v104, v86
	v_fmac_f32_e32 v84, v105, v86
	v_fma_f32 v86, v107, v86, v33
	v_fmac_f32_e32 v74, v97, v87
	v_fmac_f32_e32 v75, v100, v87
	v_fmac_f32_e32 v83, v101, v87
	v_fmac_f32_e32 v84, v104, v87
	v_fmac_f32_e32 v86, v105, v87
	v_fma_f32 v87, v107, v87, v33
	v_fmac_f32_e32 v74, v96, v90
	v_fmac_f32_e32 v75, v97, v90
	v_fmac_f32_e32 v83, v100, v90
	v_fmac_f32_e32 v84, v101, v90
	v_fmac_f32_e32 v86, v104, v90
	v_fmac_f32_e32 v87, v105, v90
	v_fma_f32 v90, v107, v90, v33
	v_fmac_f32_e32 v74, v93, v91
	v_fmac_f32_e32 v75, v96, v91
	v_fmac_f32_e32 v83, v97, v91
	v_fmac_f32_e32 v84, v100, v91
	v_fmac_f32_e32 v86, v101, v91
	v_fmac_f32_e32 v87, v104, v91
	v_fmac_f32_e32 v90, v105, v91
	v_fma_f32 v91, v107, v91, v33
	v_fmac_f32_e32 v74, v92, v94
	v_fmac_f32_e32 v75, v93, v94
	v_fmac_f32_e32 v83, v96, v94
	v_fmac_f32_e32 v84, v97, v94
	v_fmac_f32_e32 v86, v100, v94
	v_fmac_f32_e32 v87, v101, v94
	v_fmac_f32_e32 v90, v104, v94
	v_fmac_f32_e32 v91, v105, v94
	v_fma_f32 v94, v107, v94, v33
	v_fmac_f32_e32 v74, v89, v95
	v_fmac_f32_e32 v75, v92, v95
	v_fmac_f32_e32 v83, v93, v95
	v_fmac_f32_e32 v84, v96, v95
	v_fmac_f32_e32 v86, v97, v95
	v_fmac_f32_e32 v87, v100, v95
	v_fmac_f32_e32 v90, v101, v95
	v_fmac_f32_e32 v91, v104, v95
	v_fmac_f32_e32 v94, v105, v95
	v_fma_f32 v95, v107, v95, v33
	v_fmac_f32_e32 v74, v88, v98
	v_fmac_f32_e32 v75, v89, v98
	v_fmac_f32_e32 v83, v92, v98
	v_fmac_f32_e32 v84, v93, v98
	v_fmac_f32_e32 v86, v96, v98
	v_fmac_f32_e32 v87, v97, v98
	v_fmac_f32_e32 v90, v100, v98
	v_fmac_f32_e32 v91, v101, v98
	v_fmac_f32_e32 v94, v104, v98
	v_fmac_f32_e32 v95, v105, v98
	v_fma_f32 v98, v107, v98, v33
	v_fmac_f32_e32 v74, v85, v99
	v_fmac_f32_e32 v75, v88, v99
	v_fmac_f32_e32 v83, v89, v99
	v_fmac_f32_e32 v84, v92, v99
	v_fmac_f32_e32 v86, v93, v99
	v_fmac_f32_e32 v87, v96, v99
	v_fmac_f32_e32 v90, v97, v99
	v_fmac_f32_e32 v91, v100, v99
	v_fmac_f32_e32 v94, v101, v99
	v_fmac_f32_e32 v95, v104, v99
	v_fmac_f32_e32 v98, v105, v99
	v_fma_f32 v99, v107, v99, v33
	v_fmac_f32_e32 v74, v82, v102
	v_fmac_f32_e32 v75, v85, v102
	v_fmac_f32_e32 v83, v88, v102
	v_fmac_f32_e32 v84, v89, v102
	v_fmac_f32_e32 v86, v92, v102
	v_fmac_f32_e32 v87, v93, v102
	v_fmac_f32_e32 v90, v96, v102
	v_fmac_f32_e32 v91, v97, v102
	v_fmac_f32_e32 v94, v100, v102
	v_fmac_f32_e32 v95, v101, v102
	v_fmac_f32_e32 v98, v104, v102
	v_fmac_f32_e32 v99, v105, v102
	v_fma_f32 v102, v107, v102, v33
	v_fmac_f32_e32 v74, v81, v103
	v_fmac_f32_e32 v75, v82, v103
	v_fmac_f32_e32 v83, v85, v103
	v_fmac_f32_e32 v84, v88, v103
	v_fmac_f32_e32 v86, v89, v103
	v_fmac_f32_e32 v87, v92, v103
	v_fmac_f32_e32 v90, v93, v103
	v_fmac_f32_e32 v91, v96, v103
	v_fmac_f32_e32 v94, v97, v103
	v_fmac_f32_e32 v95, v100, v103
	v_fmac_f32_e32 v98, v101, v103
	v_fmac_f32_e32 v99, v104, v103
	v_fmac_f32_e32 v102, v105, v103
	v_fma_f32 v103, v107, v103, v33
	v_fmac_f32_e32 v74, v80, v108
	v_fmac_f32_e32 v75, v81, v108
	v_fmac_f32_e32 v83, v82, v108
	v_fmac_f32_e32 v84, v85, v108
	v_fmac_f32_e32 v86, v88, v108
	v_fmac_f32_e32 v87, v89, v108
	v_fmac_f32_e32 v90, v92, v108
	v_fmac_f32_e32 v91, v93, v108
	v_fmac_f32_e32 v94, v96, v108
	v_fmac_f32_e32 v95, v97, v108
	v_fmac_f32_e32 v98, v100, v108
	v_fmac_f32_e32 v99, v101, v108
	v_fmac_f32_e32 v102, v104, v108
	v_fmac_f32_e32 v103, v105, v108
	v_fmac_f32_e32 v74, v79, v109
	v_fmac_f32_e32 v75, v80, v109
	v_fmac_f32_e32 v83, v81, v109
	v_fmac_f32_e32 v84, v82, v109
	v_fmac_f32_e32 v86, v85, v109
	v_fmac_f32_e32 v87, v88, v109
	v_fmac_f32_e32 v90, v89, v109
	v_fmac_f32_e32 v91, v92, v109
	v_fmac_f32_e32 v94, v93, v109
	v_fmac_f32_e32 v95, v96, v109
	v_fmac_f32_e32 v98, v97, v109
	v_fmac_f32_e32 v99, v100, v109
	v_fmac_f32_e32 v102, v101, v109
	v_fmac_f32_e32 v103, v104, v109
	v_fmac_f32_e32 v33, v107, v109
	ds_read2st64_b32 v[108:109], v40 offset0:32 offset1:34
	s_waitcnt lgkmcnt(0)
; __device__ __forceinline__ void conv_phase(LAS unsigned char* lds, const bf16_t* P, const float* cw, const float* cb, const float* ng, const float* nb, bf16_t* CAT, int bid, int G, const int tid) {
;     ...
;             for (int i = 0; i < 46; ++i) {
;                 const float z = zs[(tb * 16 + i) * 128 + c];
; #pragma unroll
;                 for (int o = 0; o < 16; ++o) { const int j = i - o; if (j >= 0 && j <= 30) acc[o] += wj[j] * z; }
	v_fmac_f32_e32 v33, v105, v108
	v_fmac_f32_e32 v106, v104, v108
	v_fmac_f32_e32 v33, v104, v109
	ds_read2st64_b32 v[104:105], v40 offset0:36 offset1:38
	v_fmac_f32_e32 v103, v101, v108
	v_fmac_f32_e32 v106, v101, v109
	v_fmac_f32_e32 v102, v100, v108
	v_fmac_f32_e32 v103, v100, v109
	s_waitcnt lgkmcnt(0)
	v_fmac_f32_e32 v33, v101, v104
	v_fmac_f32_e32 v106, v100, v104
	v_fmac_f32_e32 v33, v100, v105
	ds_read2st64_b32 v[100:101], v40 offset0:40 offset1:42
	v_fmac_f32_e32 v99, v97, v108
	v_fmac_f32_e32 v102, v97, v109
	v_fmac_f32_e32 v103, v97, v104
	v_fmac_f32_e32 v106, v97, v105
	s_waitcnt lgkmcnt(0)
	v_fmac_f32_e32 v33, v97, v100
	v_fmac_f32_e32 v98, v96, v108
	v_fmac_f32_e32 v99, v96, v109
	v_fmac_f32_e32 v102, v96, v104
	v_fmac_f32_e32 v103, v96, v105
	v_fmac_f32_e32 v106, v96, v100
	v_fmac_f32_e32 v33, v96, v101
	ds_read2st64_b32 v[96:97], v40 offset0:44 offset1:46
	v_fmac_f32_e32 v95, v93, v108
	v_fmac_f32_e32 v98, v93, v109
	v_fmac_f32_e32 v99, v93, v104
	v_fmac_f32_e32 v102, v93, v105
	v_fmac_f32_e32 v103, v93, v100
	v_fmac_f32_e32 v106, v93, v101
	s_waitcnt lgkmcnt(0)
	v_fmac_f32_e32 v33, v93, v96
	v_fmac_f32_e32 v94, v92, v108
	v_fmac_f32_e32 v95, v92, v109
	v_fmac_f32_e32 v98, v92, v104
	v_fmac_f32_e32 v99, v92, v105
	v_fmac_f32_e32 v102, v92, v100
	v_fmac_f32_e32 v103, v92, v101
	v_fmac_f32_e32 v106, v92, v96
	v_fmac_f32_e32 v33, v92, v97
	ds_read2st64_b32 v[92:93], v40 offset0:48 offset1:50
	v_fmac_f32_e32 v74, v78, v108
	v_fmac_f32_e32 v75, v79, v108
	v_fmac_f32_e32 v83, v80, v108
	v_fmac_f32_e32 v84, v81, v108
	v_fmac_f32_e32 v86, v82, v108
	v_fmac_f32_e32 v87, v85, v108
	v_fmac_f32_e32 v90, v88, v108
	v_fmac_f32_e32 v91, v89, v108
	v_fmac_f32_e32 v74, v77, v109
	v_fmac_f32_e32 v75, v78, v109
	v_fmac_f32_e32 v83, v79, v109
	v_fmac_f32_e32 v84, v80, v109
	v_fmac_f32_e32 v86, v81, v109
	v_fmac_f32_e32 v87, v82, v109
	v_fmac_f32_e32 v90, v85, v109
	v_fmac_f32_e32 v91, v88, v109
	v_fmac_f32_e32 v94, v89, v109
	v_fmac_f32_e32 v74, v76, v104
	v_fmac_f32_e32 v75, v77, v104
	v_fmac_f32_e32 v83, v78, v104
	v_fmac_f32_e32 v84, v79, v104
	v_fmac_f32_e32 v86, v80, v104
	v_fmac_f32_e32 v87, v81, v104
	v_fmac_f32_e32 v90, v82, v104
	v_fmac_f32_e32 v91, v85, v104
	v_fmac_f32_e32 v94, v88, v104
	v_fmac_f32_e32 v95, v89, v104
	v_fmac_f32_e32 v74, v73, v105
	v_fmac_f32_e32 v75, v76, v105
	v_fmac_f32_e32 v83, v77, v105
	v_fmac_f32_e32 v84, v78, v105
	v_fmac_f32_e32 v86, v79, v105
	v_fmac_f32_e32 v87, v80, v105
	v_fmac_f32_e32 v90, v81, v105
	v_fmac_f32_e32 v91, v82, v105
	v_fmac_f32_e32 v94, v85, v105
	v_fmac_f32_e32 v95, v88, v105
	v_fmac_f32_e32 v98, v89, v105
	v_fmac_f32_e32 v74, v72, v100
	v_fmac_f32_e32 v75, v73, v100
	v_fmac_f32_e32 v83, v76, v100
	v_fmac_f32_e32 v84, v77, v100
	v_fmac_f32_e32 v86, v78, v100
	v_fmac_f32_e32 v87, v79, v100
	v_fmac_f32_e32 v90, v80, v100
	v_fmac_f32_e32 v91, v81, v100
	v_fmac_f32_e32 v94, v82, v100
	v_fmac_f32_e32 v95, v85, v100
	v_fmac_f32_e32 v98, v88, v100
	v_fmac_f32_e32 v99, v89, v100
	v_fmac_f32_e32 v102, v89, v101
	v_fmac_f32_e32 v103, v89, v96
	v_fmac_f32_e32 v106, v89, v97
	s_waitcnt lgkmcnt(0)
	v_fmac_f32_e32 v33, v89, v92
	v_fmac_f32_e32 v74, v71, v101
	v_fmac_f32_e32 v75, v72, v101
	v_fmac_f32_e32 v83, v73, v101
	v_fmac_f32_e32 v84, v76, v101
	v_fmac_f32_e32 v86, v77, v101
	v_fmac_f32_e32 v87, v78, v101
	v_fmac_f32_e32 v90, v79, v101
	v_fmac_f32_e32 v91, v80, v101
	v_fmac_f32_e32 v94, v81, v101
	v_fmac_f32_e32 v95, v82, v101
	v_fmac_f32_e32 v98, v85, v101
	v_fmac_f32_e32 v99, v88, v101
	v_fmac_f32_e32 v102, v88, v96
	v_fmac_f32_e32 v103, v88, v97
	v_fmac_f32_e32 v106, v88, v92
	v_fmac_f32_e32 v33, v88, v93
	ds_read2st64_b32 v[88:89], v40 offset0:52 offset1:54
	v_fmac_f32_e32 v74, v70, v96
	v_fmac_f32_e32 v75, v71, v96
	v_fmac_f32_e32 v83, v72, v96
	v_fmac_f32_e32 v84, v73, v96
	v_fmac_f32_e32 v86, v76, v96
	v_fmac_f32_e32 v87, v77, v96
	v_fmac_f32_e32 v90, v78, v96
	v_fmac_f32_e32 v91, v79, v96
	v_fmac_f32_e32 v94, v80, v96
	v_fmac_f32_e32 v95, v81, v96
	v_fmac_f32_e32 v98, v82, v96
	v_fmac_f32_e32 v99, v85, v96
	v_fmac_f32_e32 v74, v69, v97
	v_fmac_f32_e32 v75, v70, v97
	v_fmac_f32_e32 v83, v71, v97
	v_fmac_f32_e32 v84, v72, v97
	v_fmac_f32_e32 v86, v73, v97
	v_fmac_f32_e32 v87, v76, v97
	v_fmac_f32_e32 v90, v77, v97
	v_fmac_f32_e32 v91, v78, v97
	v_fmac_f32_e32 v94, v79, v97
	v_fmac_f32_e32 v95, v80, v97
	v_fmac_f32_e32 v98, v81, v97
	v_fmac_f32_e32 v99, v82, v97
	v_fmac_f32_e32 v102, v85, v97
	v_fmac_f32_e32 v74, v68, v92
	v_fmac_f32_e32 v75, v69, v92
	v_fmac_f32_e32 v83, v70, v92
	v_fmac_f32_e32 v84, v71, v92
	v_fmac_f32_e32 v86, v72, v92
	v_fmac_f32_e32 v87, v73, v92
	v_fmac_f32_e32 v90, v76, v92
	v_fmac_f32_e32 v91, v77, v92
	v_fmac_f32_e32 v94, v78, v92
	v_fmac_f32_e32 v95, v79, v92
	v_fmac_f32_e32 v98, v80, v92
	v_fmac_f32_e32 v99, v81, v92
	v_fmac_f32_e32 v102, v82, v92
	v_fmac_f32_e32 v103, v85, v92
	v_fmac_f32_e32 v74, v67, v93
	v_fmac_f32_e32 v75, v68, v93
	v_fmac_f32_e32 v83, v69, v93
	v_fmac_f32_e32 v84, v70, v93
	v_fmac_f32_e32 v86, v71, v93
	v_fmac_f32_e32 v87, v72, v93
	v_fmac_f32_e32 v90, v73, v93
	v_fmac_f32_e32 v91, v76, v93
	v_fmac_f32_e32 v94, v77, v93
	v_fmac_f32_e32 v95, v78, v93
	v_fmac_f32_e32 v98, v79, v93
	v_fmac_f32_e32 v99, v80, v93
	v_fmac_f32_e32 v102, v81, v93
	v_fmac_f32_e32 v103, v82, v93
	v_fmac_f32_e32 v106, v85, v93
	s_waitcnt lgkmcnt(0)
; __device__ __forceinline__ void conv_phase(LAS unsigned char* lds, const bf16_t* P, const float* cw, const float* cb, const float* ng, const float* nb, bf16_t* CAT, int bid, int G, const int tid) {
;     ...
;             for (int i = 0; i < 46; ++i) {
;                 const float z = zs[(tb * 16 + i) * 128 + c];
; #pragma unroll
;                 for (int o = 0; o < 16; ++o) { const int j = i - o; if (j >= 0 && j <= 30) acc[o] += wj[j] * z; }
	v_fmac_f32_e32 v74, v66, v88
	v_fmac_f32_e32 v75, v67, v88
	v_fmac_f32_e32 v83, v68, v88
	v_fmac_f32_e32 v84, v69, v88
	v_fmac_f32_e32 v86, v70, v88
	v_fmac_f32_e32 v87, v71, v88
	v_fmac_f32_e32 v90, v72, v88
	v_fmac_f32_e32 v91, v73, v88
	v_fmac_f32_e32 v94, v76, v88
	v_fmac_f32_e32 v95, v77, v88
	v_fmac_f32_e32 v98, v78, v88
	v_fmac_f32_e32 v99, v79, v88
	v_fmac_f32_e32 v102, v80, v88
	v_fmac_f32_e32 v103, v81, v88
	v_fmac_f32_e32 v106, v82, v88
	v_fmac_f32_e32 v33, v85, v88
	v_fmac_f32_e32 v74, v34, v89
	v_fmac_f32_e32 v75, v66, v89
	v_fmac_f32_e32 v83, v67, v89
	v_fmac_f32_e32 v84, v68, v89
	v_fmac_f32_e32 v86, v69, v89
	v_fmac_f32_e32 v87, v70, v89
	v_fmac_f32_e32 v90, v71, v89
	v_fmac_f32_e32 v91, v72, v89
	v_fmac_f32_e32 v94, v73, v89
	v_fmac_f32_e32 v95, v76, v89
	v_fmac_f32_e32 v98, v77, v89
	v_fmac_f32_e32 v99, v78, v89
	v_fmac_f32_e32 v102, v79, v89
	v_fmac_f32_e32 v103, v80, v89
	v_fmac_f32_e32 v106, v81, v89
	v_fmac_f32_e32 v33, v82, v89
	ds_read2st64_b32 v[88:89], v40 offset0:56 offset1:58
	s_waitcnt lgkmcnt(0)
	v_fmac_f32_e32 v33, v81, v88
	v_fmac_f32_e32 v106, v80, v88
	v_fmac_f32_e32 v33, v80, v89
	ds_read2st64_b32 v[80:81], v40 offset0:60 offset1:62
	v_fmac_f32_e32 v103, v79, v88
	v_fmac_f32_e32 v106, v79, v89
	v_fmac_f32_e32 v102, v78, v88
	v_fmac_f32_e32 v103, v78, v89
	s_waitcnt lgkmcnt(0)
	v_fmac_f32_e32 v33, v79, v80
	v_fmac_f32_e32 v106, v78, v80
	v_fmac_f32_e32 v33, v78, v81
	ds_read2st64_b32 v[78:79], v40 offset0:64 offset1:66
	v_fmac_f32_e32 v99, v77, v88
	v_fmac_f32_e32 v102, v77, v89
	v_fmac_f32_e32 v103, v77, v80
	v_fmac_f32_e32 v106, v77, v81
	s_waitcnt lgkmcnt(0)
	v_fmac_f32_e32 v33, v77, v78
	v_fmac_f32_e32 v98, v76, v88
	v_fmac_f32_e32 v99, v76, v89
	v_fmac_f32_e32 v102, v76, v80
	v_fmac_f32_e32 v103, v76, v81
	v_fmac_f32_e32 v106, v76, v78
	v_fmac_f32_e32 v33, v76, v79
	ds_read2st64_b32 v[76:77], v40 offset0:68 offset1:70
	v_fmac_f32_e32 v95, v73, v88
	v_fmac_f32_e32 v98, v73, v89
	v_fmac_f32_e32 v99, v73, v80
	v_fmac_f32_e32 v102, v73, v81
	v_fmac_f32_e32 v103, v73, v78
	v_fmac_f32_e32 v106, v73, v79
	s_waitcnt lgkmcnt(0)
	v_fmac_f32_e32 v33, v73, v76
	v_fmac_f32_e32 v94, v72, v88
	v_fmac_f32_e32 v95, v72, v89
	v_fmac_f32_e32 v98, v72, v80
	v_fmac_f32_e32 v99, v72, v81
	v_fmac_f32_e32 v102, v72, v78
	v_fmac_f32_e32 v103, v72, v79
	v_fmac_f32_e32 v106, v72, v76
	v_fmac_f32_e32 v33, v72, v77
	ds_read2st64_b32 v[72:73], v40 offset0:72 offset1:74
	v_fmac_f32_e32 v91, v71, v88
	v_fmac_f32_e32 v94, v71, v89
	v_fmac_f32_e32 v95, v71, v80
	v_fmac_f32_e32 v98, v71, v81
	v_fmac_f32_e32 v99, v71, v78
	v_fmac_f32_e32 v102, v71, v79
	v_fmac_f32_e32 v103, v71, v76
	v_fmac_f32_e32 v106, v71, v77
	s_waitcnt lgkmcnt(0)
	v_fmac_f32_e32 v33, v71, v72
	v_fmac_f32_e32 v90, v70, v88
	v_fmac_f32_e32 v91, v70, v89
	v_fmac_f32_e32 v94, v70, v80
	v_fmac_f32_e32 v95, v70, v81
	v_fmac_f32_e32 v98, v70, v78
	v_fmac_f32_e32 v99, v70, v79
	v_fmac_f32_e32 v102, v70, v76
	v_fmac_f32_e32 v103, v70, v77
	v_fmac_f32_e32 v106, v70, v72
	v_fmac_f32_e32 v33, v70, v73
	ds_read2st64_b32 v[70:71], v40 offset0:76 offset1:78
	v_fmac_f32_e32 v87, v69, v88
	v_fmac_f32_e32 v90, v69, v89
	v_fmac_f32_e32 v91, v69, v80
	v_fmac_f32_e32 v94, v69, v81
	v_fmac_f32_e32 v95, v69, v78
	v_fmac_f32_e32 v98, v69, v79
	v_fmac_f32_e32 v99, v69, v76
	v_fmac_f32_e32 v102, v69, v77
	v_fmac_f32_e32 v103, v69, v72
	v_fmac_f32_e32 v106, v69, v73
	s_waitcnt lgkmcnt(0)
	v_fmac_f32_e32 v33, v69, v70
	v_fmac_f32_e32 v86, v68, v88
	v_fmac_f32_e32 v87, v68, v89
	v_fmac_f32_e32 v90, v68, v80
	v_fmac_f32_e32 v91, v68, v81
	v_fmac_f32_e32 v94, v68, v78
	v_fmac_f32_e32 v95, v68, v79
	v_fmac_f32_e32 v98, v68, v76
	v_fmac_f32_e32 v99, v68, v77
	v_fmac_f32_e32 v102, v68, v72
	v_fmac_f32_e32 v103, v68, v73
	v_fmac_f32_e32 v106, v68, v70
	v_fmac_f32_e32 v33, v68, v71
	ds_read2st64_b32 v[68:69], v40 offset0:80 offset1:82
	v_fmac_f32_e32 v84, v67, v88
	v_fmac_f32_e32 v86, v67, v89
	v_fmac_f32_e32 v87, v67, v80
	v_fmac_f32_e32 v90, v67, v81
	v_fmac_f32_e32 v91, v67, v78
	v_fmac_f32_e32 v94, v67, v79
	v_fmac_f32_e32 v95, v67, v76
	v_fmac_f32_e32 v98, v67, v77
	v_fmac_f32_e32 v99, v67, v72
	v_fmac_f32_e32 v102, v67, v73
	v_fmac_f32_e32 v103, v67, v70
	v_fmac_f32_e32 v106, v67, v71
	s_waitcnt lgkmcnt(0)
	v_fmac_f32_e32 v33, v67, v68
	v_fmac_f32_e32 v83, v66, v88
	v_fmac_f32_e32 v84, v66, v89
	v_fmac_f32_e32 v86, v66, v80
	v_fmac_f32_e32 v87, v66, v81
	v_fmac_f32_e32 v90, v66, v78
	v_fmac_f32_e32 v91, v66, v79
	v_fmac_f32_e32 v94, v66, v76
	v_fmac_f32_e32 v95, v66, v77
	v_fmac_f32_e32 v98, v66, v72
	v_fmac_f32_e32 v99, v66, v73
	v_fmac_f32_e32 v102, v66, v70
	v_fmac_f32_e32 v103, v66, v71
	v_fmac_f32_e32 v106, v66, v68
	v_fmac_f32_e32 v33, v66, v69
	ds_read2st64_b32 v[66:67], v40 offset0:84 offset1:86
	v_fmac_f32_e32 v75, v34, v88
	v_fmac_f32_e32 v83, v34, v89
	v_fmac_f32_e32 v84, v34, v80
	v_fmac_f32_e32 v86, v34, v81
	v_fmac_f32_e32 v87, v34, v78
	v_fmac_f32_e32 v90, v34, v79
	v_fmac_f32_e32 v91, v34, v76
	v_fmac_f32_e32 v94, v34, v77
	v_fmac_f32_e32 v95, v34, v72
	v_fmac_f32_e32 v98, v34, v73
	v_fmac_f32_e32 v99, v34, v70
	v_fmac_f32_e32 v102, v34, v71
	v_fmac_f32_e32 v103, v34, v68
	v_fmac_f32_e32 v106, v34, v69
	s_waitcnt lgkmcnt(0)
; #define LAS __attribute__((address_space(3)))
; __device__ __forceinline__ void conv_phase(LAS unsigned char* lds, const bf16_t* P, const float* cw, const float* cb, const float* ng, const float* nb, bf16_t* CAT, int bid, int G, const int tid) {
;     ...
;                 for (int o = 0; o < 16; ++o) { const int j = i - o; if (j >= 0 && j <= 30) acc[o] += wj[j] * z; }
;             }
; #pragma unroll
;             for (int o = 0; o < 16; ++o) co[(tb * 16 + o) * 128 + c] = acc[o];
;         }
;         __syncthreads();
;         {
;             const f32x2 gg = *(const f32x2*)(ng + g * 128 + 2 * lane), bb = *(const f32x2*)(nb + g * 128 + 2 * lane);
; #pragma unroll
;             for (int k = 0; k < 8; ++k) {
;                 const int tok = w * 8 + k;
;                 const f32x2 v = *(const LAS f32x2*)(co + tok * 128 + 2 * lane);
;                 const float mean = wave_sum(v[0] + v[1]) * (1.0f / 128.0f);
	v_fmac_f32_e32 v33, v34, v66
	v_fmac_f32_e32 v74, v35, v88
	v_fmac_f32_e32 v75, v35, v89
	v_fmac_f32_e32 v83, v35, v80
	v_fmac_f32_e32 v84, v35, v81
	v_fmac_f32_e32 v86, v35, v78
	v_fmac_f32_e32 v87, v35, v79
	v_fmac_f32_e32 v90, v35, v76
	v_fmac_f32_e32 v91, v35, v77
	v_fmac_f32_e32 v94, v35, v72
	v_fmac_f32_e32 v95, v35, v73
	v_fmac_f32_e32 v98, v35, v70
	v_fmac_f32_e32 v99, v35, v71
	v_fmac_f32_e32 v102, v35, v68
	v_fmac_f32_e32 v103, v35, v69
	v_fmac_f32_e32 v106, v35, v66
	v_fmac_f32_e32 v33, v35, v67
	ds_read2st64_b32 v[34:35], v40 offset0:88 offset1:90
	v_fmac_f32_e32 v74, v31, v89
	v_fmac_f32_e32 v75, v31, v80
	v_fmac_f32_e32 v74, v32, v80
	v_fmac_f32_e32 v75, v32, v81
	v_fmac_f32_e32 v83, v31, v81
	v_fmac_f32_e32 v84, v31, v78
	v_fmac_f32_e32 v86, v31, v79
	v_fmac_f32_e32 v87, v31, v76
	v_fmac_f32_e32 v90, v31, v77
	v_fmac_f32_e32 v91, v31, v72
	v_fmac_f32_e32 v94, v31, v73
	v_fmac_f32_e32 v95, v31, v70
	v_fmac_f32_e32 v98, v31, v71
	v_fmac_f32_e32 v99, v31, v68
	v_fmac_f32_e32 v102, v31, v69
	v_fmac_f32_e32 v103, v31, v66
	v_fmac_f32_e32 v106, v31, v67
	s_waitcnt lgkmcnt(0)
	v_fmac_f32_e32 v33, v31, v34
	v_fmac_f32_e32 v83, v32, v78
	v_fmac_f32_e32 v84, v32, v79
	v_fmac_f32_e32 v86, v32, v76
	v_fmac_f32_e32 v87, v32, v77
	v_fmac_f32_e32 v90, v32, v72
	v_fmac_f32_e32 v91, v32, v73
	v_fmac_f32_e32 v94, v32, v70
	v_fmac_f32_e32 v95, v32, v71
	v_fmac_f32_e32 v98, v32, v68
	v_fmac_f32_e32 v99, v32, v69
	v_fmac_f32_e32 v102, v32, v66
	v_fmac_f32_e32 v103, v32, v67
	v_fmac_f32_e32 v106, v32, v34
	v_fmac_f32_e32 v33, v32, v35
	ds_write2st64_b32 v40, v74, v75 offset0:188 offset1:190
	ds_write2st64_b32 v40, v83, v84 offset0:192 offset1:194
	ds_write2st64_b32 v40, v86, v87 offset0:196 offset1:198
	ds_write2st64_b32 v40, v90, v91 offset0:200 offset1:202
	ds_write2st64_b32 v40, v94, v95 offset0:204 offset1:206
	ds_write2st64_b32 v40, v98, v99 offset0:208 offset1:210
	ds_write2st64_b32 v40, v102, v103 offset0:212 offset1:214
	ds_write2st64_b32 v40, v106, v33 offset0:216 offset1:218
	s_waitcnt lgkmcnt(0)
	s_barrier
	v_lshl_add_u64 v[32:33], v[26:27], 0, s[26:27]
	global_load_dwordx2 v[34:35], v[32:33], off
	v_lshl_add_u64 v[32:33], v[28:29], 0, s[26:27]
	global_load_dwordx2 v[32:33], v[32:33], off
	s_lshl_b32 s26, s30, 1
	v_mov_b32_e32 v31, v177
	ds_read_b64 v[110:111], v58 offset:48128
	ds_read_b64 v[112:113], v59 offset:48128
	ds_read_b64 v[114:115], v60 offset:48128
	ds_read_b64 v[116:117], v61 offset:48128
	ds_read_b64 v[118:119], v62 offset:48128
	ds_read_b64 v[120:121], v63 offset:48128
	ds_read_b64 v[122:123], v64 offset:48128
	ds_read_b64 v[124:125], v65 offset:48128
	s_waitcnt lgkmcnt(7)
	v_add_f32_e32 v126, v110, v111
	s_waitcnt lgkmcnt(6)
	v_add_f32_e32 v127, v112, v113
	s_waitcnt lgkmcnt(5)
	v_add_f32_e32 v128, v114, v115
	s_waitcnt lgkmcnt(4)
	v_add_f32_e32 v129, v116, v117
	s_waitcnt lgkmcnt(3)
	v_add_f32_e32 v130, v118, v119
	s_waitcnt lgkmcnt(2)
	v_add_f32_e32 v131, v120, v121
	s_waitcnt lgkmcnt(1)
	v_add_f32_e32 v132, v122, v123
	s_waitcnt lgkmcnt(0)
	v_add_f32_e32 v133, v124, v125
	ds_bpermute_b32 v134, v42, v126
	ds_bpermute_b32 v135, v42, v127
	ds_bpermute_b32 v136, v42, v128
	ds_bpermute_b32 v137, v42, v129
	ds_bpermute_b32 v138, v42, v130
	ds_bpermute_b32 v139, v42, v131
	ds_bpermute_b32 v140, v42, v132
	ds_bpermute_b32 v141, v42, v133
	s_waitcnt lgkmcnt(7)
	v_add_f32_e32 v126, v126, v134
	s_waitcnt lgkmcnt(6)
	v_add_f32_e32 v127, v127, v135
	s_waitcnt lgkmcnt(5)
	v_add_f32_e32 v128, v128, v136
	s_waitcnt lgkmcnt(4)
	v_add_f32_e32 v129, v129, v137
	s_waitcnt lgkmcnt(3)
	v_add_f32_e32 v130, v130, v138
	s_waitcnt lgkmcnt(2)
	v_add_f32_e32 v131, v131, v139
	s_waitcnt lgkmcnt(1)
	v_add_f32_e32 v132, v132, v140
	s_waitcnt lgkmcnt(0)
	v_add_f32_e32 v133, v133, v141
	ds_bpermute_b32 v134, v43, v126
	ds_bpermute_b32 v135, v43, v127
	ds_bpermute_b32 v136, v43, v128
	ds_bpermute_b32 v137, v43, v129
	ds_bpermute_b32 v138, v43, v130
	ds_bpermute_b32 v139, v43, v131
	ds_bpermute_b32 v140, v43, v132
	ds_bpermute_b32 v141, v43, v133
	s_waitcnt lgkmcnt(7)
	v_add_f32_e32 v126, v126, v134
	s_waitcnt lgkmcnt(6)
	v_add_f32_e32 v127, v127, v135
	s_waitcnt lgkmcnt(5)
	v_add_f32_e32 v128, v128, v136
	s_waitcnt lgkmcnt(4)
	v_add_f32_e32 v129, v129, v137
	s_waitcnt lgkmcnt(3)
	v_add_f32_e32 v130, v130, v138
	s_waitcnt lgkmcnt(2)
	v_add_f32_e32 v131, v131, v139
	s_waitcnt lgkmcnt(1)
	v_add_f32_e32 v132, v132, v140
	s_waitcnt lgkmcnt(0)
	v_add_f32_e32 v133, v133, v141
	ds_bpermute_b32 v134, v44, v126
	ds_bpermute_b32 v135, v44, v127
	ds_bpermute_b32 v136, v44, v128
	ds_bpermute_b32 v137, v44, v129
	ds_bpermute_b32 v138, v44, v130
	ds_bpermute_b32 v139, v44, v131
	ds_bpermute_b32 v140, v44, v132
	ds_bpermute_b32 v141, v44, v133
	s_waitcnt lgkmcnt(7)
	v_add_f32_e32 v126, v126, v134
	s_waitcnt lgkmcnt(6)
	v_add_f32_e32 v127, v127, v135
	s_waitcnt lgkmcnt(5)
	v_add_f32_e32 v128, v128, v136
	s_waitcnt lgkmcnt(4)
	v_add_f32_e32 v129, v129, v137
	s_waitcnt lgkmcnt(3)
	v_add_f32_e32 v130, v130, v138
	s_waitcnt lgkmcnt(2)
	v_add_f32_e32 v131, v131, v139
	s_waitcnt lgkmcnt(1)
	v_add_f32_e32 v132, v132, v140
	s_waitcnt lgkmcnt(0)
	v_add_f32_e32 v133, v133, v141
	ds_bpermute_b32 v134, v45, v126
	ds_bpermute_b32 v135, v45, v127
	ds_bpermute_b32 v136, v45, v128
	ds_bpermute_b32 v137, v45, v129
	ds_bpermute_b32 v138, v45, v130
	ds_bpermute_b32 v139, v45, v131
	ds_bpermute_b32 v140, v45, v132
	ds_bpermute_b32 v141, v45, v133
	s_waitcnt lgkmcnt(7)
	v_add_f32_e32 v126, v126, v134
	s_waitcnt lgkmcnt(6)
	v_add_f32_e32 v127, v127, v135
	s_waitcnt lgkmcnt(5)
	v_add_f32_e32 v128, v128, v136
	s_waitcnt lgkmcnt(4)
	v_add_f32_e32 v129, v129, v137
	s_waitcnt lgkmcnt(3)
; __device__ __forceinline__ void conv_phase(LAS unsigned char* lds, const bf16_t* P, const float* cw, const float* cb, const float* ng, const float* nb, bf16_t* CAT, int bid, int G, const int tid) {
;     ...
;                 const float mean = wave_sum(v[0] + v[1]) * (1.0f / 128.0f);
;                 const float d0 = v[0] - mean, d1 = v[1] - mean;
;                 const float rs = __builtin_amdgcn_rsqf(wave_sum(d0 * d0 + d1 * d1) * (1.0f / 128.0f) + EPS);
	v_add_f32_e32 v130, v130, v138
	s_waitcnt lgkmcnt(2)
	v_add_f32_e32 v131, v131, v139
	s_waitcnt lgkmcnt(1)
	v_add_f32_e32 v132, v132, v140
	s_waitcnt lgkmcnt(0)
	v_add_f32_e32 v133, v133, v141
	ds_bpermute_b32 v134, v46, v126
	ds_bpermute_b32 v135, v46, v127
	ds_bpermute_b32 v136, v46, v128
	ds_bpermute_b32 v137, v46, v129
	ds_bpermute_b32 v138, v46, v130
	ds_bpermute_b32 v139, v46, v131
	ds_bpermute_b32 v140, v46, v132
	ds_bpermute_b32 v141, v46, v133
	s_waitcnt lgkmcnt(7)
	v_add_f32_e32 v126, v126, v134
	s_waitcnt lgkmcnt(6)
	v_add_f32_e32 v127, v127, v135
	s_waitcnt lgkmcnt(5)
	v_add_f32_e32 v128, v128, v136
	s_waitcnt lgkmcnt(4)
	v_add_f32_e32 v129, v129, v137
	s_waitcnt lgkmcnt(3)
	v_add_f32_e32 v130, v130, v138
	s_waitcnt lgkmcnt(2)
	v_add_f32_e32 v131, v131, v139
	s_waitcnt lgkmcnt(1)
	v_add_f32_e32 v132, v132, v140
	s_waitcnt lgkmcnt(0)
	v_add_f32_e32 v133, v133, v141
	ds_bpermute_b32 v134, v47, v126
	ds_bpermute_b32 v135, v47, v127
	ds_bpermute_b32 v136, v47, v128
	ds_bpermute_b32 v137, v47, v129
	ds_bpermute_b32 v138, v47, v130
	ds_bpermute_b32 v139, v47, v131
	ds_bpermute_b32 v140, v47, v132
	ds_bpermute_b32 v141, v47, v133
	s_waitcnt lgkmcnt(7)
	v_add_f32_e32 v126, v126, v134
	s_waitcnt lgkmcnt(6)
	v_add_f32_e32 v127, v127, v135
	s_waitcnt lgkmcnt(5)
	v_add_f32_e32 v128, v128, v136
	s_waitcnt lgkmcnt(4)
	v_add_f32_e32 v129, v129, v137
	s_waitcnt lgkmcnt(3)
	v_add_f32_e32 v130, v130, v138
	s_waitcnt lgkmcnt(2)
	v_add_f32_e32 v131, v131, v139
	s_waitcnt lgkmcnt(1)
	v_add_f32_e32 v132, v132, v140
	s_waitcnt lgkmcnt(0)
	v_add_f32_e32 v133, v133, v141
	v_fmac_f32_e32 v111, 0xbc000000, v126
	v_fmamk_f32 v110, v126, 0xbc000000, v110
	v_fmac_f32_e32 v113, 0xbc000000, v127
	v_fmamk_f32 v112, v127, 0xbc000000, v112
	v_fmac_f32_e32 v115, 0xbc000000, v128
	v_fmamk_f32 v114, v128, 0xbc000000, v114
	v_fmac_f32_e32 v117, 0xbc000000, v129
	v_fmamk_f32 v116, v129, 0xbc000000, v116
	v_fmac_f32_e32 v119, 0xbc000000, v130
	v_fmamk_f32 v118, v130, 0xbc000000, v118
	v_fmac_f32_e32 v121, 0xbc000000, v131
	v_fmamk_f32 v120, v131, 0xbc000000, v120
	v_fmac_f32_e32 v123, 0xbc000000, v132
	v_fmamk_f32 v122, v132, 0xbc000000, v122
	v_fmac_f32_e32 v125, 0xbc000000, v133
	v_fmamk_f32 v124, v133, 0xbc000000, v124
	v_mul_f32_e32 v126, v111, v111
	v_fmac_f32_e32 v126, v110, v110
	v_mul_f32_e32 v127, v113, v113
	v_fmac_f32_e32 v127, v112, v112
	v_mul_f32_e32 v128, v115, v115
	v_fmac_f32_e32 v128, v114, v114
	v_mul_f32_e32 v129, v117, v117
	v_fmac_f32_e32 v129, v116, v116
	v_mul_f32_e32 v130, v119, v119
	v_fmac_f32_e32 v130, v118, v118
	v_mul_f32_e32 v131, v121, v121
	v_fmac_f32_e32 v131, v120, v120
	v_mul_f32_e32 v132, v123, v123
	v_fmac_f32_e32 v132, v122, v122
	v_mul_f32_e32 v133, v125, v125
	v_fmac_f32_e32 v133, v124, v124
	ds_bpermute_b32 v134, v42, v126
	ds_bpermute_b32 v135, v42, v127
	ds_bpermute_b32 v136, v42, v128
	ds_bpermute_b32 v137, v42, v129
	ds_bpermute_b32 v138, v42, v130
	ds_bpermute_b32 v139, v42, v131
	ds_bpermute_b32 v140, v42, v132
	ds_bpermute_b32 v141, v42, v133
	s_waitcnt lgkmcnt(7)
	v_add_f32_e32 v126, v126, v134
	s_waitcnt lgkmcnt(6)
	v_add_f32_e32 v127, v127, v135
	s_waitcnt lgkmcnt(5)
	v_add_f32_e32 v128, v128, v136
	s_waitcnt lgkmcnt(4)
	v_add_f32_e32 v129, v129, v137
	s_waitcnt lgkmcnt(3)
	v_add_f32_e32 v130, v130, v138
	s_waitcnt lgkmcnt(2)
	v_add_f32_e32 v131, v131, v139
	s_waitcnt lgkmcnt(1)
	v_add_f32_e32 v132, v132, v140
	s_waitcnt lgkmcnt(0)
	v_add_f32_e32 v133, v133, v141
	ds_bpermute_b32 v134, v43, v126
	ds_bpermute_b32 v135, v43, v127
	ds_bpermute_b32 v136, v43, v128
	ds_bpermute_b32 v137, v43, v129
	ds_bpermute_b32 v138, v43, v130
	ds_bpermute_b32 v139, v43, v131
	ds_bpermute_b32 v140, v43, v132
	ds_bpermute_b32 v141, v43, v133
	s_waitcnt lgkmcnt(7)
	v_add_f32_e32 v126, v126, v134
	s_waitcnt lgkmcnt(6)
	v_add_f32_e32 v127, v127, v135
	s_waitcnt lgkmcnt(5)
	v_add_f32_e32 v128, v128, v136
	s_waitcnt lgkmcnt(4)
	v_add_f32_e32 v129, v129, v137
	s_waitcnt lgkmcnt(3)
	v_add_f32_e32 v130, v130, v138
	s_waitcnt lgkmcnt(2)
	v_add_f32_e32 v131, v131, v139
	s_waitcnt lgkmcnt(1)
	v_add_f32_e32 v132, v132, v140
	s_waitcnt lgkmcnt(0)
	v_add_f32_e32 v133, v133, v141
	ds_bpermute_b32 v134, v44, v126
	ds_bpermute_b32 v135, v44, v127
	ds_bpermute_b32 v136, v44, v128
	ds_bpermute_b32 v137, v44, v129
	ds_bpermute_b32 v138, v44, v130
	ds_bpermute_b32 v139, v44, v131
	ds_bpermute_b32 v140, v44, v132
	ds_bpermute_b32 v141, v44, v133
	s_waitcnt lgkmcnt(7)
	v_add_f32_e32 v126, v126, v134
	s_waitcnt lgkmcnt(6)
	v_add_f32_e32 v127, v127, v135
	s_waitcnt lgkmcnt(5)
	v_add_f32_e32 v128, v128, v136
	s_waitcnt lgkmcnt(4)
	v_add_f32_e32 v129, v129, v137
	s_waitcnt lgkmcnt(3)
	v_add_f32_e32 v130, v130, v138
	s_waitcnt lgkmcnt(2)
	v_add_f32_e32 v131, v131, v139
	s_waitcnt lgkmcnt(1)
	v_add_f32_e32 v132, v132, v140
	s_waitcnt lgkmcnt(0)
	v_add_f32_e32 v133, v133, v141
	ds_bpermute_b32 v134, v45, v126
	ds_bpermute_b32 v135, v45, v127
	ds_bpermute_b32 v136, v45, v128
	ds_bpermute_b32 v137, v45, v129
	ds_bpermute_b32 v138, v45, v130
	ds_bpermute_b32 v139, v45, v131
	ds_bpermute_b32 v140, v45, v132
	ds_bpermute_b32 v141, v45, v133
	s_waitcnt lgkmcnt(7)
	v_add_f32_e32 v126, v126, v134
	s_waitcnt lgkmcnt(6)
	v_add_f32_e32 v127, v127, v135
	s_waitcnt lgkmcnt(5)
	v_add_f32_e32 v128, v128, v136
	s_waitcnt lgkmcnt(4)
	v_add_f32_e32 v129, v129, v137
	s_waitcnt lgkmcnt(3)
	v_add_f32_e32 v130, v130, v138
	s_waitcnt lgkmcnt(2)
	v_add_f32_e32 v131, v131, v139
	s_waitcnt lgkmcnt(1)
	v_add_f32_e32 v132, v132, v140
	s_waitcnt lgkmcnt(0)
; __device__ __forceinline__ void conv_phase(LAS unsigned char* lds, const bf16_t* P, const float* cw, const float* cb, const float* ng, const float* nb, bf16_t* CAT, int bid, int G, const int tid) {
;     ...
;                 const float rs = __builtin_amdgcn_rsqf(wave_sum(d0 * d0 + d1 * d1) * (1.0f / 128.0f) + EPS);
;                 const float y0 = d0 * rs * gg[0] + bb[0], y1 = d1 * rs * gg[1] + bb[1];
	v_add_f32_e32 v133, v133, v141
	ds_bpermute_b32 v134, v46, v126
	ds_bpermute_b32 v135, v46, v127
	ds_bpermute_b32 v136, v46, v128
	ds_bpermute_b32 v137, v46, v129
	ds_bpermute_b32 v138, v46, v130
	ds_bpermute_b32 v139, v46, v131
	ds_bpermute_b32 v140, v46, v132
	ds_bpermute_b32 v141, v46, v133
	s_waitcnt lgkmcnt(7)
	v_add_f32_e32 v126, v126, v134
	s_waitcnt lgkmcnt(6)
	v_add_f32_e32 v127, v127, v135
	s_waitcnt lgkmcnt(5)
	v_add_f32_e32 v128, v128, v136
	s_waitcnt lgkmcnt(4)
	v_add_f32_e32 v129, v129, v137
	s_waitcnt lgkmcnt(3)
	v_add_f32_e32 v130, v130, v138
	s_waitcnt lgkmcnt(2)
	v_add_f32_e32 v131, v131, v139
	s_waitcnt lgkmcnt(1)
	v_add_f32_e32 v132, v132, v140
	s_waitcnt lgkmcnt(0)
	v_add_f32_e32 v133, v133, v141
	ds_bpermute_b32 v134, v47, v126
	ds_bpermute_b32 v135, v47, v127
	ds_bpermute_b32 v136, v47, v128
	ds_bpermute_b32 v137, v47, v129
	ds_bpermute_b32 v138, v47, v130
	ds_bpermute_b32 v139, v47, v131
	ds_bpermute_b32 v140, v47, v132
	ds_bpermute_b32 v141, v47, v133
	s_waitcnt lgkmcnt(7)
	v_add_f32_e32 v126, v126, v134
	s_waitcnt lgkmcnt(6)
	v_add_f32_e32 v127, v127, v135
	s_waitcnt lgkmcnt(5)
	v_add_f32_e32 v128, v128, v136
	s_waitcnt lgkmcnt(4)
	v_add_f32_e32 v129, v129, v137
	s_waitcnt lgkmcnt(3)
	v_add_f32_e32 v130, v130, v138
	s_waitcnt lgkmcnt(2)
	v_add_f32_e32 v131, v131, v139
	s_waitcnt lgkmcnt(1)
	v_add_f32_e32 v132, v132, v140
	s_waitcnt lgkmcnt(0)
	v_add_f32_e32 v133, v133, v141
	v_fmamk_f32 v126, v126, 0x3c000000, v189
	v_fmamk_f32 v127, v127, 0x3c000000, v189
	v_fmamk_f32 v128, v128, 0x3c000000, v189
	v_fmamk_f32 v129, v129, 0x3c000000, v189
	v_fmamk_f32 v130, v130, 0x3c000000, v189
	v_fmamk_f32 v131, v131, 0x3c000000, v189
	v_fmamk_f32 v132, v132, 0x3c000000, v189
	v_fmamk_f32 v133, v133, 0x3c000000, v189
	v_rsq_f32_e32 v126, v126
	v_rsq_f32_e32 v127, v127
	v_rsq_f32_e32 v128, v128
	v_rsq_f32_e32 v129, v129
	v_rsq_f32_e32 v130, v130
	v_rsq_f32_e32 v131, v131
	v_rsq_f32_e32 v132, v132
	v_rsq_f32_e32 v133, v133
	s_waitcnt vmcnt(0)
; #define LAS __attribute__((address_space(3)))
; __device__ __forceinline__ unsigned cvt_pk_bf16(float lo, float hi) { unsigned r; asm("v_cvt_pk_bf16_f32 %0, %1, %2" : "=v"(r) : "v"(lo), "v"(hi)); return r; }
; __device__ __forceinline__ float silu_f(float x) { return x * fast_sigmoid(x); }
; __device__ __forceinline__ void conv_phase(LAS unsigned char* lds, const bf16_t* P, const float* cw, const float* cb, const float* ng, const float* nb, bf16_t* CAT, int bid, int G, const int tid) {
;     ...
;             const f32x2 gg = *(const f32x2*)(ng + g * 128 + 2 * lane), bb = *(const f32x2*)(nb + g * 128 + 2 * lane);
; #pragma unroll
;             for (int k = 0; k < 8; ++k) {
;                 const int tok = w * 8 + k;
;                 const f32x2 v = *(const LAS f32x2*)(co + tok * 128 + 2 * lane);
;                 const float mean = wave_sum(v[0] + v[1]) * (1.0f / 128.0f);
;                 const float d0 = v[0] - mean, d1 = v[1] - mean;
;                 const float rs = __builtin_amdgcn_rsqf(wave_sum(d0 * d0 + d1 * d1) * (1.0f / 128.0f) + EPS);
;                 const float y0 = d0 * rs * gg[0] + bb[0], y1 = d1 * rs * gg[1] + bb[1];
;                 *(unsigned*)(CAT + (size_t)(b * SEQ + t0 + tok) * D + 1024 + g * 128 + 2 * lane) = cvt_pk_bf16(silu_f(y0), silu_f(y1));
	v_mul_f32_e32 v110, v110, v126
	v_mul_f32_e32 v111, v111, v126
	v_mul_f32_e32 v112, v112, v127
	v_mul_f32_e32 v113, v113, v127
	v_mul_f32_e32 v114, v114, v128
	v_mul_f32_e32 v115, v115, v128
	v_mul_f32_e32 v116, v116, v129
	v_mul_f32_e32 v117, v117, v129
	v_mul_f32_e32 v118, v118, v130
	v_mul_f32_e32 v119, v119, v130
	v_mul_f32_e32 v120, v120, v131
	v_mul_f32_e32 v121, v121, v131
	v_mul_f32_e32 v122, v122, v132
	v_mul_f32_e32 v123, v123, v132
	v_mul_f32_e32 v124, v124, v133
	v_mul_f32_e32 v125, v125, v133
	v_fma_f32 v110, v34, v110, v32
	v_fma_f32 v111, v35, v111, v33
	v_fma_f32 v112, v34, v112, v32
	v_fma_f32 v113, v35, v113, v33
	v_fma_f32 v114, v34, v114, v32
	v_fma_f32 v115, v35, v115, v33
	v_fma_f32 v116, v34, v116, v32
	v_fma_f32 v117, v35, v117, v33
	v_fma_f32 v118, v34, v118, v32
	v_fma_f32 v119, v35, v119, v33
	v_fma_f32 v120, v34, v120, v32
	v_fma_f32 v121, v35, v121, v33
	v_fma_f32 v122, v34, v122, v32
	v_fma_f32 v123, v35, v123, v33
	v_fma_f32 v124, v34, v124, v32
	v_fma_f32 v125, v35, v125, v33
	v_mul_f32_e32 v134, 0xbfb8aa3b, v110
	v_mul_f32_e32 v142, 0xbfb8aa3b, v111
	v_mul_f32_e32 v135, 0xbfb8aa3b, v112
	v_mul_f32_e32 v143, 0xbfb8aa3b, v113
	v_mul_f32_e32 v136, 0xbfb8aa3b, v114
	v_mul_f32_e32 v144, 0xbfb8aa3b, v115
	v_mul_f32_e32 v137, 0xbfb8aa3b, v116
	v_mul_f32_e32 v145, 0xbfb8aa3b, v117
	v_mul_f32_e32 v138, 0xbfb8aa3b, v118
	v_mul_f32_e32 v146, 0xbfb8aa3b, v119
	v_mul_f32_e32 v139, 0xbfb8aa3b, v120
	v_mul_f32_e32 v147, 0xbfb8aa3b, v121
	v_mul_f32_e32 v140, 0xbfb8aa3b, v122
	v_mul_f32_e32 v148, 0xbfb8aa3b, v123
	v_mul_f32_e32 v141, 0xbfb8aa3b, v124
	v_mul_f32_e32 v149, 0xbfb8aa3b, v125
	v_exp_f32_e32 v134, v134
	v_exp_f32_e32 v142, v142
	v_exp_f32_e32 v135, v135
	v_exp_f32_e32 v143, v143
	v_exp_f32_e32 v136, v136
	v_exp_f32_e32 v144, v144
	v_exp_f32_e32 v137, v137
	v_exp_f32_e32 v145, v145
	v_exp_f32_e32 v138, v138
	v_exp_f32_e32 v146, v146
	v_exp_f32_e32 v139, v139
	v_exp_f32_e32 v147, v147
	v_exp_f32_e32 v140, v140
	v_exp_f32_e32 v148, v148
	v_exp_f32_e32 v141, v141
	v_exp_f32_e32 v149, v149
	s_nop 0
	v_add_f32_e32 v134, 1.0, v134
	v_add_f32_e32 v142, 1.0, v142
	v_add_f32_e32 v135, 1.0, v135
	v_add_f32_e32 v143, 1.0, v143
	v_add_f32_e32 v136, 1.0, v136
	v_add_f32_e32 v144, 1.0, v144
	v_add_f32_e32 v137, 1.0, v137
	v_add_f32_e32 v145, 1.0, v145
	v_add_f32_e32 v138, 1.0, v138
	v_add_f32_e32 v146, 1.0, v146
	v_add_f32_e32 v139, 1.0, v139
	v_add_f32_e32 v147, 1.0, v147
	v_add_f32_e32 v140, 1.0, v140
	v_add_f32_e32 v148, 1.0, v148
	v_add_f32_e32 v141, 1.0, v141
	v_add_f32_e32 v149, 1.0, v149
	v_rcp_f32_e32 v134, v134
	v_rcp_f32_e32 v142, v142
	v_rcp_f32_e32 v135, v135
	v_rcp_f32_e32 v143, v143
	v_rcp_f32_e32 v136, v136
	v_rcp_f32_e32 v144, v144
	v_rcp_f32_e32 v137, v137
	v_rcp_f32_e32 v145, v145
	v_rcp_f32_e32 v138, v138
	v_rcp_f32_e32 v146, v146
	v_rcp_f32_e32 v139, v139
	v_rcp_f32_e32 v147, v147
	v_rcp_f32_e32 v140, v140
	v_rcp_f32_e32 v148, v148
	v_rcp_f32_e32 v141, v141
	v_rcp_f32_e32 v149, v149
	s_nop 0
	v_mul_f32_e32 v110, v110, v134
	v_mul_f32_e32 v111, v111, v142
	v_mul_f32_e32 v112, v112, v135
	v_mul_f32_e32 v113, v113, v143
	v_mul_f32_e32 v114, v114, v136
	v_mul_f32_e32 v115, v115, v144
	v_mul_f32_e32 v116, v116, v137
	v_mul_f32_e32 v117, v117, v145
	v_mul_f32_e32 v118, v118, v138
	v_mul_f32_e32 v119, v119, v146
	v_mul_f32_e32 v120, v120, v139
	v_mul_f32_e32 v121, v121, v147
	v_mul_f32_e32 v122, v122, v140
	v_mul_f32_e32 v123, v123, v148
	v_mul_f32_e32 v124, v124, v141
	v_mul_f32_e32 v125, v125, v149
	v_cvt_pk_bf16_f32 v134, v110, v111
	v_cvt_pk_bf16_f32 v135, v112, v113
	v_cvt_pk_bf16_f32 v136, v114, v115
	v_cvt_pk_bf16_f32 v137, v116, v117
	v_cvt_pk_bf16_f32 v138, v118, v119
	v_cvt_pk_bf16_f32 v139, v120, v121
	v_cvt_pk_bf16_f32 v140, v122, v123
	v_cvt_pk_bf16_f32 v141, v124, v125
	v_add_u32_e32 v66, s31, v41
	v_ashrrev_i32_e32 v67, 31, v66
	v_lshlrev_b64 v[66:67], 12, v[66:67]
	v_lshl_add_u64 v[66:67], s[92:93], 0, v[66:67]
	v_lshl_add_u64 v[66:67], v[66:67], 0, s[26:27]
	v_lshl_add_u64 v[66:67], v[66:67], 0, v[30:31]
	global_store_dword v[66:67], v134, off offset:2048
	v_add_u32_e32 v66, s31, v51
	v_ashrrev_i32_e32 v67, 31, v66
	v_lshlrev_b64 v[66:67], 12, v[66:67]
	v_lshl_add_u64 v[66:67], s[92:93], 0, v[66:67]
	v_lshl_add_u64 v[66:67], v[66:67], 0, s[26:27]
	v_lshl_add_u64 v[66:67], v[66:67], 0, v[30:31]
	global_store_dword v[66:67], v135, off offset:2048
	v_add_u32_e32 v66, s31, v52
	v_ashrrev_i32_e32 v67, 31, v66
	v_lshlrev_b64 v[66:67], 12, v[66:67]
	v_lshl_add_u64 v[66:67], s[92:93], 0, v[66:67]
	v_lshl_add_u64 v[66:67], v[66:67], 0, s[26:27]
	v_lshl_add_u64 v[66:67], v[66:67], 0, v[30:31]
	global_store_dword v[66:67], v136, off offset:2048
	v_add_u32_e32 v66, s31, v53
	v_ashrrev_i32_e32 v67, 31, v66
	v_lshlrev_b64 v[66:67], 12, v[66:67]
	v_lshl_add_u64 v[66:67], s[92:93], 0, v[66:67]
	v_lshl_add_u64 v[66:67], v[66:67], 0, s[26:27]
	v_lshl_add_u64 v[66:67], v[66:67], 0, v[30:31]
	global_store_dword v[66:67], v137, off offset:2048
	v_add_u32_e32 v66, s31, v54
	v_ashrrev_i32_e32 v67, 31, v66
	v_lshlrev_b64 v[66:67], 12, v[66:67]
	v_lshl_add_u64 v[66:67], s[92:93], 0, v[66:67]
	v_lshl_add_u64 v[66:67], v[66:67], 0, s[26:27]
	v_lshl_add_u64 v[66:67], v[66:67], 0, v[30:31]
	global_store_dword v[66:67], v138, off offset:2048
	v_add_u32_e32 v66, s31, v55
	v_ashrrev_i32_e32 v67, 31, v66
	v_lshlrev_b64 v[66:67], 12, v[66:67]
	v_lshl_add_u64 v[66:67], s[92:93], 0, v[66:67]
	v_lshl_add_u64 v[66:67], v[66:67], 0, s[26:27]
	v_lshl_add_u64 v[66:67], v[66:67], 0, v[30:31]
	global_store_dword v[66:67], v139, off offset:2048
	v_add_u32_e32 v66, s31, v56
	v_ashrrev_i32_e32 v67, 31, v66
	v_lshlrev_b64 v[66:67], 12, v[66:67]
	v_lshl_add_u64 v[66:67], s[92:93], 0, v[66:67]
	v_lshl_add_u64 v[66:67], v[66:67], 0, s[26:27]
	v_lshl_add_u64 v[66:67], v[66:67], 0, v[30:31]
	global_store_dword v[66:67], v140, off offset:2048
	v_add_u32_e32 v66, s31, v57
	v_ashrrev_i32_e32 v67, 31, v66
	v_lshlrev_b64 v[66:67], 12, v[66:67]
	v_lshl_add_u64 v[66:67], s[92:93], 0, v[66:67]
	v_lshl_add_u64 v[66:67], v[66:67], 0, s[26:27]
	v_lshl_add_u64 v[66:67], v[66:67], 0, v[30:31]
	global_store_dword v[66:67], v141, off offset:2048
	s_cbranch_vccz .LBB0_186

; __device__ __forceinline__ void conv_phase(LAS unsigned char* lds, const bf16_t* P, const float* cw, const float* cb, const float* ng, const float* nb, bf16_t* CAT, int bid, int G, const int tid) {
;     ...
;         if (u + G < 4096) CONV_LOAD(u + G);
.LBB0_177:
	s_andn2_b64 vcc, exec, s[30:31]
	s_cbranch_vccnz .LBB0_170
	s_add_i32 s15, s16, s34
	s_and_b32 s17, s15, 0x7c0
	s_sub_i32 s45, s17, 30
	s_add_i32 s17, s3, s35
	s_and_b32 s26, s17, 0x380
	s_waitcnt vmcnt(0)
	v_add_u32_e32 v5, s45, v36
	v_mov_b32_e32 v2, v177
	v_mov_b32_e32 v3, v177
	s_lshl_b32 s26, s26, 1
	v_cmp_lt_i32_e32 vcc, -1, v5
	v_mov_b32_e32 v0, v177
	v_mov_b32_e32 v1, v177
	v_mov_b64_e32 v[14:15], v[2:3]
	s_and_b32 s44, s15, 0xfffff800
	v_lshl_add_u64 v[32:33], v[24:25], 0, s[26:27]
	s_and_b64 s[46:47], s[38:39], vcc
	v_mov_b32_e32 v4, 0
	v_mov_b64_e32 v[12:13], v[0:1]
	v_mov_b32_e32 v8, 0
	v_mov_b32_e32 v9, 0
	v_mov_b32_e32 v10, 0
	v_mov_b32_e32 v11, 0
	s_and_saveexec_b64 s[30:31], s[46:47]
	s_cbranch_execz .LBB0_180
	v_add_u32_e32 v5, s44, v5
	v_mad_i64_i32 v[6:7], s[46:47], v5, s48, v[32:33]
	v_add_co_u32_e32 v12, vcc, 0x1000, v6
	s_nop 1
	v_addc_co_u32_e32 v13, vcc, 0, v7, vcc
	global_load_dwordx4 v[8:11], v[6:7], off offset:2176
	s_nop 0
	global_load_dwordx4 v[12:15], v[12:13], off offset:128
.LBB0_180:
	s_or_b64 exec, exec, s[30:31]
	v_add_u32_e32 v16, s45, v37
	v_cmp_lt_i32_e32 vcc, -1, v16
	s_and_b64 s[46:47], s[40:41], vcc
	v_mov_b32_e32 v5, 0
	v_mov_b32_e32 v6, 0
	v_mov_b32_e32 v7, 0
	s_and_saveexec_b64 s[30:31], s[46:47]
	s_cbranch_execz .LBB0_182
	v_add_u32_e32 v0, s44, v16
	v_mad_i64_i32 v[0:1], s[46:47], v0, s48, v[32:33]
	v_add_co_u32_e32 v2, vcc, 0x1000, v0
	s_nop 1
	v_addc_co_u32_e32 v3, vcc, 0, v1, vcc
	global_load_dwordx4 v[4:7], v[0:1], off offset:2176
	s_nop 0
	global_load_dwordx4 v[0:3], v[2:3], off offset:128
.LBB0_182:
	s_or_b64 exec, exec, s[30:31]
	v_add_u32_e32 v31, s45, v38
	v_cmp_lt_i32_e32 vcc, -1, v31
	s_and_b64 s[46:47], s[42:43], vcc
	v_mov_b32_e32 v19, 0
	v_mov_b32_e32 v18, 0
	v_mov_b32_e32 v17, 0
	v_mov_b32_e32 v16, 0
	v_mov_b32_e32 v23, 0
	v_mov_b32_e32 v22, 0
	v_mov_b32_e32 v21, 0
	v_mov_b32_e32 v20, 0
	s_and_saveexec_b64 s[30:31], s[46:47]
	s_cbranch_execz .LBB0_169
	v_add_u32_e32 v16, s44, v31
	v_mad_i64_i32 v[16:17], s[44:45], v16, s48, v[32:33]
	v_add_co_u32_e32 v20, vcc, 0x1000, v16
	s_nop 1
	v_addc_co_u32_e32 v21, vcc, 0, v17, vcc
	global_load_dwordx4 v[16:19], v[16:17], off offset:2176
	s_nop 0
	global_load_dwordx4 v[20:23], v[20:21], off offset:128
	s_branch .LBB0_169
